# SSM pass 1: 30 of the 32 E^T weight fragments register-resident for the item, in the chunk loop and in the peeled last chunk
# baseline (speedup 1.0000x reference)
; #define LAS __attribute__((address_space(3)))
; template <bool PASS2>
; __device__ __forceinline__ void ssm_phase(const Params& p, const Frame& F0) {
;     ...
;         __syncthreads();
;         { const u32x4* src = (const u32x4*)((const bf16_t*)(p.ws + WS_SSMW) + (size_t)g * SSM_FRAG_ELEMS);
;           for (int e = F.tid; e < SSM_FRAG_ELEMS / 8; e += 512) ((LAS u32x4*)F.lds)[e] = src[e];
;           if (F.tid < 64) ((LAS f32x2*)(F.lds + SSM_M1_OFF))[F.tid] = ((const f32x2*)(p.ws + WS_M1))[g * 64 + F.tid]; }
;         __syncthreads();
;         const LAS bf16x8* frag = (const LAS bf16x8*)F.lds + lane;
;         const LAS f32x4* m1t = (const LAS f32x4*)(F.lds + SSM_M1_OFF) + 2 * gq;
;         const int b = subset >> 2, wch = (subset & 3) * 8 + F.wave;
;         f32x4 xs[8];
; #pragma unroll
;         for (int i = 0; i < 8; ++i) xs[i] = (f32x4){0.f, 0.f, 0.f, 0.f};
;     ...
;         bf16x8 uf[4], ufn[4]; u32x2 uw[8], uwn[8];
;         SSM_LOAD_U(uf, uw, 0)
;         for (int cc = 0; cc < nch; ++cc) {
;             asm volatile("" ::: "memory");
;             const bool samp = (cc == 4);
;             const int row0 = SSM_ROW0(cc), nsub = SSM_NSUB(cc), js = jsamp;
;             if (samp) {
; #pragma unroll
;                 for (int i = 0; i < 4; ++i) { xs[i] = *(const f32x4*)(p.in[2] + (size_t)(js * NG + g) * 64 + 16 * i + 4 * gq); xs[i + 4] = *(const f32x4*)(p.in[3] + (size_t)(js * NG + g) * 64 + 16 * i + 4 * gq); } }
;             if (cc + 1 < nch) SSM_LOAD_U(ufn, uwn, cc + 1)
;             unsigned hw[4][4];
; #pragma unroll
;             for (int i = 0; i < 4; ++i) {
;                 __builtin_amdgcn_sched_barrier(0);
;                 f32x4 Er = (f32x4){0.f, 0.f, 0.f, 0.f}, Ei = Er;
; #pragma unroll
;                 for (int ks = 0; ks < 4; ++ks) { Er = __builtin_amdgcn_mfma_f32_16x16x32_bf16(frag[(i * 4 + ks) * 64], uf[ks], Er, 0, 0, 0);
;                                                  Ei = __builtin_amdgcn_mfma_f32_16x16x32_bf16(frag[((i + 4) * 4 + ks) * 64], uf[ks], Ei, 0, 0, 0); }
;                 const f32x4 ma = m1t[8 * i], mb = m1t[8 * i + 1];
;                 float mr[4] = {ma[0], ma[2], mb[0], mb[2]}, mi[4] = {ma[1], ma[3], mb[1], mb[3]};
;                 float hr[4], hi[4];
; #pragma unroll
;                 for (int r = 0; r < 4; ++r) { hr[r] = dppf<DPP_ROR(1)>(xs[i][r]); hi[r] = dppf<DPP_ROR(1)>(xs[i + 4][r]);
.LBB0_526:
	s_or_b64 exec, exec, s[0:1]
	s_lshr_b32 s0, s23, 2
	s_and_b32 s18, s0, 24
	s_ashr_i32 s17, s23, 7
	s_add_i32 s18, s18, s3
	s_lshl_b32 s0, s17, 14
	s_lshl_b32 s1, s18, 9
	s_add_i32 s1, s1, s0
	v_or_b32_e32 v0, s1, v106
	v_or_b32_e32 v4, 2, v0
	s_lshl_b32 s10, s16, 5
	v_ashrrev_i32_e32 v1, 31, v0
	v_ashrrev_i32_e32 v5, 31, v4
	v_lshl_add_u64 v[64:65], v[38:39], 0, s[10:11]
	v_lshlrev_b64 v[2:3], 10, v[0:1]
	v_lshlrev_b64 v[4:5], 10, v[4:5]
	v_lshl_add_u64 v[2:3], v[64:65], 0, v[2:3]
	v_lshl_add_u64 v[4:5], v[64:65], 0, v[4:5]
	s_waitcnt lgkmcnt(0)
	s_barrier
	global_load_dwordx4 v[12:15], v[2:3], off
	s_nop 0
	global_load_dwordx4 v[4:7], v[4:5], off
	v_or_b32_e32 v2, 4, v0
	v_or_b32_e32 v0, 6, v0
	v_ashrrev_i32_e32 v3, 31, v2
	v_ashrrev_i32_e32 v1, 31, v0
	v_lshlrev_b64 v[2:3], 10, v[2:3]
	v_lshlrev_b64 v[0:1], 10, v[0:1]
	v_lshl_add_u64 v[2:3], v[64:65], 0, v[2:3]
	v_lshl_add_u64 v[0:1], v[64:65], 0, v[0:1]
	global_load_dwordx4 v[8:11], v[2:3], off
	s_nop 0
	global_load_dwordx4 v[0:3], v[0:1], off
	s_lshl_b32 s1, s23, 7
	s_and_b32 s1, s1, 0x3000
	s_or_b32 s0, s1, s0
	v_add_u32_e32 v80, s0, v37
	s_mov_b32 s0, 0
	v_mov_b32_e32 v44, 0
	v_mov_b32_e32 v45, 0
	v_mov_b32_e32 v48, 0
	v_mov_b32_e32 v49, 0
	v_mov_b32_e32 v52, 0
	v_mov_b32_e32 v53, 0
	v_mov_b32_e32 v56, 0
	v_mov_b32_e32 v57, 0
	v_mov_b32_e32 v60, 0
	v_mov_b32_e32 v61, 0
	v_mov_b32_e32 v66, 0
	v_mov_b32_e32 v67, 0
	v_mov_b32_e32 v70, 0
	v_mov_b32_e32 v71, 0
	v_mov_b32_e32 v74, 0
	v_mov_b32_e32 v75, 0
	v_mov_b32_e32 v46, 0
	v_mov_b32_e32 v47, 0
	v_mov_b32_e32 v50, 0
	v_mov_b32_e32 v51, 0
	v_mov_b32_e32 v54, 0
	v_mov_b32_e32 v55, 0
	v_mov_b32_e32 v58, 0
	v_mov_b32_e32 v59, 0
	v_mov_b32_e32 v62, 0
	v_mov_b32_e32 v63, 0
	v_mov_b32_e32 v68, 0
	v_mov_b32_e32 v69, 0
	v_mov_b32_e32 v72, 0
	v_mov_b32_e32 v73, 0
	v_mov_b32_e32 v76, 0
	v_mov_b32_e32 v77, 0
	ds_read_b128 v[130:133], v105
	ds_read_b128 v[134:137], v105 offset:1024
	ds_read_b128 v[138:141], v105 offset:2048
	ds_read_b128 v[142:145], v105 offset:3072
	ds_read_b128 v[146:149], v105 offset:4096
	ds_read_b128 v[150:153], v105 offset:5120
	ds_read_b128 v[154:157], v105 offset:6144
	ds_read_b128 v[158:161], v105 offset:7168
	ds_read_b128 v[162:165], v105 offset:8192
	ds_read_b128 v[166:169], v105 offset:9216
	ds_read_b128 v[170:173], v105 offset:10240
	ds_read_b128 v[174:177], v105 offset:11264
	ds_read_b128 v[178:181], v105 offset:12288
	ds_read_b128 v[182:185], v105 offset:13312
	ds_read_b128 v[186:189], v105 offset:14336
	ds_read_b128 v[190:193], v105 offset:15360
	ds_read_b128 v[194:197], v105 offset:16384
	ds_read_b128 v[198:201], v105 offset:17408
	ds_read_b128 v[204:207], v105 offset:18432
	ds_read_b128 v[208:211], v105 offset:19456
	ds_read_b128 v[212:215], v105 offset:20480
	ds_read_b128 v[216:219], v105 offset:21504
	ds_read_b128 v[220:223], v105 offset:22528
	ds_read_b128 v[224:227], v105 offset:23552
	ds_read_b128 v[228:231], v105 offset:24576
	ds_read_b128 v[232:235], v105 offset:25600
	ds_read_b128 v[236:239], v105 offset:26624
	ds_read_b128 v[240:243], v105 offset:27648
	ds_read_b128 v[244:247], v105 offset:28672
	ds_read_b128 v[248:251], v105 offset:29696
	s_waitcnt lgkmcnt(0)
.LBB0_527:
	s_waitcnt vmcnt(0)
	v_mov_b64_e32 v[18:19], v[2:3]
	v_mov_b64_e32 v[26:27], v[6:7]
	v_mov_b64_e32 v[16:17], v[0:1]
	v_add_u32_e32 v1, s0, v80
	v_mov_b64_e32 v[24:25], v[4:5]
	v_add_u32_e32 v0, 0x80, v1
	v_add_u32_e32 v2, 0x82, v1
	v_add_u32_e32 v4, 0x84, v1
	v_add_u32_e32 v6, 0x86, v1
	v_ashrrev_i32_e32 v1, 31, v0
	v_ashrrev_i32_e32 v3, 31, v2
	v_ashrrev_i32_e32 v5, 31, v4
	v_mov_b64_e32 v[22:23], v[10:11]
	v_ashrrev_i32_e32 v7, 31, v6
	v_lshlrev_b64 v[0:1], 10, v[0:1]
	v_lshlrev_b64 v[2:3], 10, v[2:3]
	v_lshlrev_b64 v[4:5], 10, v[4:5]
	v_mov_b64_e32 v[30:31], v[14:15]
	v_mov_b64_e32 v[20:21], v[8:9]
	v_lshlrev_b64 v[6:7], 10, v[6:7]
	v_lshl_add_u64 v[0:1], v[64:65], 0, v[0:1]
	v_lshl_add_u64 v[2:3], v[64:65], 0, v[2:3]
	v_lshl_add_u64 v[8:9], v[64:65], 0, v[4:5]
	v_mov_b64_e32 v[28:29], v[12:13]
	v_lshl_add_u64 v[32:33], v[64:65], 0, v[6:7]
	global_load_dwordx4 v[12:15], v[0:1], off
	global_load_dwordx4 v[4:7], v[2:3], off
	s_nop 0
	global_load_dwordx4 v[8:11], v[8:9], off
	s_nop 0
	global_load_dwordx4 v[0:3], v[32:33], off
	v_mov_b32_dpp v79, v72 row_ror:1 row_mask:0xf bank_mask:0xf bound_ctrl:1
	v_mov_b32_dpp v78, v70 row_ror:1 row_mask:0xf bank_mask:0xf bound_ctrl:1
	v_mov_b32_dpp v73, v73 row_ror:1 row_mask:0xf bank_mask:0xf bound_ctrl:1
	v_mov_b32_dpp v72, v71 row_ror:1 row_mask:0xf bank_mask:0xf bound_ctrl:1
	v_mfma_f32_16x16x32_bf16 v[32:35], v[130:133], v[28:31], 0
	v_mfma_f32_16x16x32_bf16 v[32:35], v[134:137], v[24:27], v[32:35]
	v_mfma_f32_16x16x32_bf16 v[82:85], v[194:197], v[28:31], 0
	v_mfma_f32_16x16x32_bf16 v[82:85], v[198:201], v[24:27], v[82:85]
	v_mfma_f32_16x16x32_bf16 v[32:35], v[138:141], v[20:23], v[32:35]
	v_mfma_f32_16x16x32_bf16 v[82:85], v[204:207], v[20:23], v[82:85]
	v_mfma_f32_16x16x32_bf16 v[86:89], v[142:145], v[16:19], v[32:35]
	s_nop 2
	v_mfma_f32_16x16x32_bf16 v[82:85], v[208:211], v[16:19], v[82:85]
	ds_read_b128 v[90:93], v109
	s_nop 0
	ds_read_b128 v[32:35], v109 offset:16
	s_waitcnt lgkmcnt(1)
	v_pk_mul_f32 v[94:95], v[90:91], v[78:79] op_sel:[0,1] op_sel_hi:[1,0]
	s_nop 0
	v_sub_f32_e32 v70, v94, v95
	v_pk_mul_f32 v[78:79], v[90:91], v[78:79]
	v_add_f32_e32 v81, v86, v70
	v_add_f32_e32 v70, v79, v78
	v_add_f32_e32 v78, v82, v70
	v_pk_mul_f32 v[70:71], v[92:93], v[72:73] op_sel:[0,1] op_sel_hi:[1,0]
	v_mov_b32_e32 v96, v91
	v_sub_f32_e32 v70, v70, v71
	v_add_f32_e32 v79, v70, v87
	v_pk_mul_f32 v[70:71], v[92:93], v[72:73]
	v_mov_b32_e32 v97, v93
	v_add_f32_e32 v70, v71, v70
	v_add_f32_e32 v94, v70, v83
	v_mov_b32_dpp v71, v76 row_ror:1 row_mask:0xf bank_mask:0xf bound_ctrl:1
	v_mov_b32_dpp v70, v74 row_ror:1 row_mask:0xf bank_mask:0xf bound_ctrl:1
	s_waitcnt lgkmcnt(0)
; #define SSM_SCAN_STEP(D, SQ) { _Pragma("unroll") for (int r = 0; r < 4; ++r) { \
;                     const float sr = dppf<DPP_SHR(D)>(Er[r]), si = dppf<DPP_SHR(D)>(Ei[r]); \
;                     Er[r] += mr[r] * sr - mi[r] * si; Ei[r] += mr[r] * si + mi[r] * sr; \
;                     if (SQ) { const float nr = mr[r] * mr[r] - mi[r] * mi[r], ni = 2.f * mr[r] * mi[r]; mr[r] = nr; mi[r] = ni; } } }
; template <bool PASS2>
; __device__ __forceinline__ void ssm_phase(const Params& p, const Frame& F0) {
;     ...
;                 const f32x4 ma = m1t[8 * i], mb = m1t[8 * i + 1];
;                 float mr[4] = {ma[0], ma[2], mb[0], mb[2]}, mi[4] = {ma[1], ma[3], mb[1], mb[3]};
;                 float hr[4], hi[4];
; #pragma unroll
;                 for (int r = 0; r < 4; ++r) { hr[r] = dppf<DPP_ROR(1)>(xs[i][r]); hi[r] = dppf<DPP_ROR(1)>(xs[i + 4][r]);
;                     if (j == 0) { Er[r] += mr[r] * hr[r] - mi[r] * hi[r]; Ei[r] += mr[r] * hi[r] + mi[r] * hr[r]; } }
;     ...
;                 SSM_SCAN_STEP(1, 1) SSM_SCAN_STEP(2, 1) SSM_SCAN_STEP(4, 1) SSM_SCAN_STEP(8, 0)
	v_pk_mul_f32 v[72:73], v[32:33], v[70:71] op_sel:[0,1] op_sel_hi:[1,0]
	v_pk_mul_f32 v[70:71], v[32:33], v[70:71]
	v_sub_f32_e32 v72, v72, v73
	v_add_f32_e32 v70, v71, v70
	v_add_f32_e32 v76, v70, v84
	v_mov_b32_dpp v71, v77 row_ror:1 row_mask:0xf bank_mask:0xf bound_ctrl:1
	v_mov_b32_dpp v70, v75 row_ror:1 row_mask:0xf bank_mask:0xf bound_ctrl:1
	v_add_f32_e32 v74, v72, v88
	v_pk_mul_f32 v[72:73], v[34:35], v[70:71] op_sel:[0,1] op_sel_hi:[1,0]
	v_pk_mul_f32 v[70:71], v[34:35], v[70:71]
	v_sub_f32_e32 v72, v72, v73
	v_add_f32_e32 v70, v71, v70
	v_add_f32_e32 v70, v70, v85
	v_add_f32_e32 v72, v72, v89
	v_cndmask_b32_e64 v85, v85, v70, s[6:7]
	v_cndmask_b32_e64 v71, v83, v94, s[6:7]
	v_cndmask_b32_e64 v70, v82, v78, s[6:7]
	v_cndmask_b32_e64 v75, v89, v72, s[6:7]
	v_cndmask_b32_e64 v74, v88, v74, s[6:7]
	v_cndmask_b32_e64 v73, v87, v79, s[6:7]
	v_cndmask_b32_e64 v72, v86, v81, s[6:7]
	v_mov_b32_dpp v86, v70 row_shr:1 row_mask:0xf bank_mask:0xf bound_ctrl:1
	v_mov_b32_dpp v87, v71 row_shr:1 row_mask:0xf bank_mask:0xf bound_ctrl:1
	v_mov_b32_e32 v88, v90
	v_mov_b32_e32 v89, v92
	v_mov_b32_dpp v82, v72 row_shr:1 row_mask:0xf bank_mask:0xf bound_ctrl:1
	v_mov_b32_dpp v83, v73 row_shr:1 row_mask:0xf bank_mask:0xf bound_ctrl:1
	v_pk_mul_f32 v[94:95], v[88:89], v[86:87]
	v_pk_mul_f32 v[92:93], v[92:93], v[92:93]
	v_pk_fma_f32 v[94:95], v[96:97], v[82:83], v[94:95]
	v_pk_mul_f32 v[90:91], v[90:91], v[90:91]
	v_pk_add_f32 v[70:71], v[94:95], v[70:71]
	v_mov_b32_e32 v94, v90
	v_mov_b32_e32 v95, v92
	v_mov_b32_e32 v92, v91
	v_pk_mul_f32 v[86:87], v[96:97], v[86:87]
	v_pk_add_f32 v[90:91], v[94:95], v[92:93] neg_lo:[0,1] neg_hi:[0,1]
	v_pk_add_f32 v[92:93], v[88:89], v[88:89]
	v_pk_fma_f32 v[82:83], v[88:89], v[82:83], v[86:87] neg_lo:[0,0,1] neg_hi:[0,0,1]
	v_pk_mul_f32 v[92:93], v[96:97], v[92:93]
	v_mov_b32_dpp v94, v70 row_shr:2 row_mask:0xf bank_mask:0xf bound_ctrl:1
	v_mov_b32_dpp v95, v71 row_shr:2 row_mask:0xf bank_mask:0xf bound_ctrl:1
	v_pk_add_f32 v[72:73], v[82:83], v[72:73]
	v_pk_mul_f32 v[98:99], v[90:91], v[94:95]
	v_pk_mul_f32 v[86:87], v[92:93], v[94:95]
	v_mov_b32_dpp v82, v72 row_shr:2 row_mask:0xf bank_mask:0xf bound_ctrl:1
	v_mov_b32_dpp v83, v73 row_shr:2 row_mask:0xf bank_mask:0xf bound_ctrl:1
	v_pk_fma_f32 v[86:87], v[90:91], v[82:83], v[86:87] neg_lo:[0,0,1] neg_hi:[0,0,1]
	v_pk_fma_f32 v[82:83], v[92:93], v[82:83], v[98:99]
	v_pk_mul_f32 v[100:101], v[92:93], v[92:93]
	v_pk_add_f32 v[102:103], v[90:91], v[90:91]
	v_pk_add_f32 v[70:71], v[70:71], v[82:83]
	v_pk_fma_f32 v[100:101], v[90:91], v[90:91], v[100:101] neg_lo:[0,0,1] neg_hi:[0,0,1]
	v_pk_mul_f32 v[102:103], v[92:93], v[102:103]
	v_pk_add_f32 v[72:73], v[86:87], v[72:73]
	v_mov_b32_dpp v86, v70 row_shr:4 row_mask:0xf bank_mask:0xf bound_ctrl:1
	v_mov_b32_dpp v87, v71 row_shr:4 row_mask:0xf bank_mask:0xf bound_ctrl:1
	v_mov_b32_dpp v82, v72 row_shr:4 row_mask:0xf bank_mask:0xf bound_ctrl:1
	v_mov_b32_dpp v83, v73 row_shr:4 row_mask:0xf bank_mask:0xf bound_ctrl:1
	v_pk_mul_f32 v[88:89], v[102:103], v[86:87]
	v_pk_mul_f32 v[86:87], v[100:101], v[86:87]
	v_pk_fma_f32 v[88:89], v[100:101], v[82:83], v[88:89] neg_lo:[0,0,1] neg_hi:[0,0,1]
	v_pk_fma_f32 v[82:83], v[102:103], v[82:83], v[86:87]
	v_pk_mul_f32 v[110:111], v[102:103], v[102:103]
	v_pk_add_f32 v[112:113], v[100:101], v[100:101]
	v_pk_add_f32 v[70:71], v[70:71], v[82:83]
	v_pk_fma_f32 v[110:111], v[100:101], v[100:101], v[110:111] neg_lo:[0,0,1] neg_hi:[0,0,1]
	v_pk_mul_f32 v[112:113], v[102:103], v[112:113]
	v_pk_add_f32 v[72:73], v[72:73], v[88:89]
	v_mov_b32_dpp v86, v70 row_shr:8 row_mask:0xf bank_mask:0xf bound_ctrl:1
	v_mov_b32_dpp v87, v71 row_shr:8 row_mask:0xf bank_mask:0xf bound_ctrl:1
	v_mov_b32_dpp v82, v72 row_shr:8 row_mask:0xf bank_mask:0xf bound_ctrl:1
	v_mov_b32_dpp v83, v73 row_shr:8 row_mask:0xf bank_mask:0xf bound_ctrl:1
	v_pk_mul_f32 v[88:89], v[112:113], v[86:87]
	v_pk_mul_f32 v[86:87], v[110:111], v[86:87]
	v_cndmask_b32_e64 v84, v84, v76, s[6:7]
	v_pk_fma_f32 v[88:89], v[110:111], v[82:83], v[88:89] neg_lo:[0,0,1] neg_hi:[0,0,1]
	v_pk_fma_f32 v[82:83], v[112:113], v[82:83], v[86:87]
	v_mov_b32_dpp v78, v84 row_shr:1 row_mask:0xf bank_mask:0xf bound_ctrl:1
	v_mov_b32_dpp v79, v85 row_shr:1 row_mask:0xf bank_mask:0xf bound_ctrl:1
	v_pk_add_f32 v[70:71], v[70:71], v[82:83]
	v_mov_b32_e32 v82, v32
	v_mov_b32_e32 v83, v34
	v_mov_b32_dpp v76, v74 row_shr:1 row_mask:0xf bank_mask:0xf bound_ctrl:1
	v_mov_b32_dpp v77, v75 row_shr:1 row_mask:0xf bank_mask:0xf bound_ctrl:1
	v_pk_add_f32 v[72:73], v[72:73], v[88:89]
	v_pk_mul_f32 v[86:87], v[82:83], v[78:79]
	v_mov_b32_e32 v88, v33
	v_mov_b32_e32 v89, v35
	v_pk_fma_f32 v[86:87], v[88:89], v[76:77], v[86:87]
	v_pk_mul_f32 v[34:35], v[34:35], v[34:35]
	v_pk_mul_f32 v[32:33], v[32:33], v[32:33]
	v_pk_mul_f32 v[78:79], v[88:89], v[78:79]
	v_pk_add_f32 v[84:85], v[86:87], v[84:85]
	v_mov_b32_e32 v86, v32
	v_mov_b32_e32 v87, v34
	v_mov_b32_e32 v34, v33
	v_pk_fma_f32 v[76:77], v[82:83], v[76:77], v[78:79] neg_lo:[0,0,1] neg_hi:[0,0,1]
	v_pk_add_f32 v[32:33], v[86:87], v[34:35] neg_lo:[0,1] neg_hi:[0,1]
	v_pk_add_f32 v[34:35], v[82:83], v[82:83]
	v_mov_b32_dpp v86, v84 row_shr:2 row_mask:0xf bank_mask:0xf bound_ctrl:1
	v_mov_b32_dpp v87, v85 row_shr:2 row_mask:0xf bank_mask:0xf bound_ctrl:1
	v_pk_add_f32 v[74:75], v[76:77], v[74:75]
	v_pk_mul_f32 v[34:35], v[88:89], v[34:35]
	v_pk_mul_f32 v[90:91], v[32:33], v[86:87]
	v_pk_add_f32 v[94:95], v[32:33], v[32:33]
	v_mov_b32_dpp v76, v74 row_shr:2 row_mask:0xf bank_mask:0xf bound_ctrl:1
	v_mov_b32_dpp v77, v75 row_shr:2 row_mask:0xf bank_mask:0xf bound_ctrl:1
	v_pk_mul_f32 v[92:93], v[34:35], v[34:35]
; #define SSM_SCAN_STEP(D, SQ) { _Pragma("unroll") for (int r = 0; r < 4; ++r) { \
;                     const float sr = dppf<DPP_SHR(D)>(Er[r]), si = dppf<DPP_SHR(D)>(Ei[r]); \
;                     Er[r] += mr[r] * sr - mi[r] * si; Ei[r] += mr[r] * si + mi[r] * sr; \
;                     if (SQ) { const float nr = mr[r] * mr[r] - mi[r] * mi[r], ni = 2.f * mr[r] * mi[r]; mr[r] = nr; mi[r] = ni; } } }
; template <bool PASS2>
; __device__ __forceinline__ void ssm_phase(const Params& p, const Frame& F0) {
;     ...
;             for (int i = 0; i < 4; ++i) {
;                 __builtin_amdgcn_sched_barrier(0);
;                 f32x4 Er = (f32x4){0.f, 0.f, 0.f, 0.f}, Ei = Er;
; #pragma unroll
;                 for (int ks = 0; ks < 4; ++ks) { Er = __builtin_amdgcn_mfma_f32_16x16x32_bf16(frag[(i * 4 + ks) * 64], uf[ks], Er, 0, 0, 0);
;                                                  Ei = __builtin_amdgcn_mfma_f32_16x16x32_bf16(frag[((i + 4) * 4 + ks) * 64], uf[ks], Ei, 0, 0, 0); }
;                 const f32x4 ma = m1t[8 * i], mb = m1t[8 * i + 1];
;                 float mr[4] = {ma[0], ma[2], mb[0], mb[2]}, mi[4] = {ma[1], ma[3], mb[1], mb[3]};
;                 float hr[4], hi[4];
; #pragma unroll
;                 for (int r = 0; r < 4; ++r) { hr[r] = dppf<DPP_ROR(1)>(xs[i][r]); hi[r] = dppf<DPP_ROR(1)>(xs[i + 4][r]);
;                     if (j == 0) { Er[r] += mr[r] * hr[r] - mi[r] * hi[r]; Ei[r] += mr[r] * hi[r] + mi[r] * hr[r]; } }
;     ...
;                 SSM_SCAN_STEP(1, 1) SSM_SCAN_STEP(2, 1) SSM_SCAN_STEP(4, 1) SSM_SCAN_STEP(8, 0)
	v_pk_mul_f32 v[94:95], v[34:35], v[94:95]
	v_pk_mul_f32 v[78:79], v[34:35], v[86:87]
	v_pk_fma_f32 v[34:35], v[34:35], v[76:77], v[90:91]
	v_pk_fma_f32 v[92:93], v[32:33], v[32:33], v[92:93] neg_lo:[0,0,1] neg_hi:[0,0,1]
	v_pk_fma_f32 v[32:33], v[32:33], v[76:77], v[78:79] neg_lo:[0,0,1] neg_hi:[0,0,1]
	v_pk_add_f32 v[34:35], v[84:85], v[34:35]
	v_pk_add_f32 v[32:33], v[74:75], v[32:33]
	v_pk_add_f32 v[98:99], v[92:93], v[92:93]
	v_mov_b32_dpp v76, v34 row_shr:4 row_mask:0xf bank_mask:0xf bound_ctrl:1
	v_mov_b32_dpp v77, v35 row_shr:4 row_mask:0xf bank_mask:0xf bound_ctrl:1
	v_mov_b32_dpp v74, v32 row_shr:4 row_mask:0xf bank_mask:0xf bound_ctrl:1
	v_mov_b32_dpp v75, v33 row_shr:4 row_mask:0xf bank_mask:0xf bound_ctrl:1
	v_pk_mul_f32 v[78:79], v[94:95], v[76:77]
	v_pk_mul_f32 v[76:77], v[92:93], v[76:77]
	v_pk_fma_f32 v[78:79], v[92:93], v[74:75], v[78:79] neg_lo:[0,0,1] neg_hi:[0,0,1]
	v_pk_fma_f32 v[74:75], v[94:95], v[74:75], v[76:77]
	v_pk_mul_f32 v[96:97], v[94:95], v[94:95]
	v_pk_add_f32 v[34:35], v[34:35], v[74:75]
	v_pk_mul_f32 v[98:99], v[94:95], v[98:99]
	v_pk_add_f32 v[32:33], v[32:33], v[78:79]
	v_mov_b32_dpp v78, v34 row_shr:8 row_mask:0xf bank_mask:0xf bound_ctrl:1
	v_mov_b32_dpp v79, v35 row_shr:8 row_mask:0xf bank_mask:0xf bound_ctrl:1
	v_pk_fma_f32 v[96:97], v[92:93], v[92:93], v[96:97] neg_lo:[0,0,1] neg_hi:[0,0,1]
	v_mov_b32_dpp v74, v32 row_shr:8 row_mask:0xf bank_mask:0xf bound_ctrl:1
	v_mov_b32_dpp v75, v33 row_shr:8 row_mask:0xf bank_mask:0xf bound_ctrl:1
	v_pk_mul_f32 v[76:77], v[98:99], v[78:79]
	s_nop 0
	v_pk_fma_f32 v[76:77], v[96:97], v[74:75], v[76:77] neg_lo:[0,0,1] neg_hi:[0,0,1]
	s_nop 0
	v_pk_add_f32 v[76:77], v[32:33], v[76:77]
	v_pk_mul_f32 v[32:33], v[96:97], v[78:79]
	s_nop 0
	v_pk_fma_f32 v[32:33], v[98:99], v[74:75], v[32:33]
	s_nop 0
	v_pk_add_f32 v[74:75], v[34:35], v[32:33]
	v_mov_b32_dpp v79, v62 row_ror:1 row_mask:0xf bank_mask:0xf bound_ctrl:1
	v_mov_b32_dpp v78, v60 row_ror:1 row_mask:0xf bank_mask:0xf bound_ctrl:1
	v_mov_b32_dpp v63, v63 row_ror:1 row_mask:0xf bank_mask:0xf bound_ctrl:1
	v_mov_b32_dpp v62, v61 row_ror:1 row_mask:0xf bank_mask:0xf bound_ctrl:1
	v_mfma_f32_16x16x32_bf16 v[32:35], v[146:149], v[28:31], 0
	v_mfma_f32_16x16x32_bf16 v[32:35], v[150:153], v[24:27], v[32:35]
	v_mfma_f32_16x16x32_bf16 v[82:85], v[212:215], v[28:31], 0
	v_mfma_f32_16x16x32_bf16 v[82:85], v[216:219], v[24:27], v[82:85]
	v_mfma_f32_16x16x32_bf16 v[32:35], v[154:157], v[20:23], v[32:35]
	v_mfma_f32_16x16x32_bf16 v[82:85], v[220:223], v[20:23], v[82:85]
	v_mfma_f32_16x16x32_bf16 v[86:89], v[158:161], v[16:19], v[32:35]
	s_nop 2
	v_mfma_f32_16x16x32_bf16 v[82:85], v[224:227], v[16:19], v[82:85]
	ds_read_b128 v[90:93], v109 offset:128
	s_nop 0
	ds_read_b128 v[32:35], v109 offset:144
	s_waitcnt lgkmcnt(1)
	v_pk_mul_f32 v[94:95], v[90:91], v[78:79] op_sel:[0,1] op_sel_hi:[1,0]
	s_nop 0
	v_sub_f32_e32 v60, v94, v95
	v_pk_mul_f32 v[78:79], v[90:91], v[78:79]
	v_add_f32_e32 v81, v86, v60
	v_add_f32_e32 v60, v79, v78
	v_add_f32_e32 v78, v82, v60
	v_pk_mul_f32 v[60:61], v[92:93], v[62:63] op_sel:[0,1] op_sel_hi:[1,0]
	v_mov_b32_e32 v96, v91
	v_sub_f32_e32 v60, v60, v61
	v_add_f32_e32 v79, v60, v87
	v_pk_mul_f32 v[60:61], v[92:93], v[62:63]
	v_mov_b32_e32 v97, v93
	v_add_f32_e32 v60, v61, v60
	v_add_f32_e32 v94, v60, v83
	v_mov_b32_dpp v61, v68 row_ror:1 row_mask:0xf bank_mask:0xf bound_ctrl:1
	v_mov_b32_dpp v60, v66 row_ror:1 row_mask:0xf bank_mask:0xf bound_ctrl:1
	s_waitcnt lgkmcnt(0)
	v_pk_mul_f32 v[62:63], v[32:33], v[60:61] op_sel:[0,1] op_sel_hi:[1,0]
	v_pk_mul_f32 v[60:61], v[32:33], v[60:61]
	v_sub_f32_e32 v62, v62, v63
	v_add_f32_e32 v60, v61, v60
	v_add_f32_e32 v68, v60, v84
	v_mov_b32_dpp v61, v69 row_ror:1 row_mask:0xf bank_mask:0xf bound_ctrl:1
	v_mov_b32_dpp v60, v67 row_ror:1 row_mask:0xf bank_mask:0xf bound_ctrl:1
	v_add_f32_e32 v66, v62, v88
	v_pk_mul_f32 v[62:63], v[34:35], v[60:61] op_sel:[0,1] op_sel_hi:[1,0]
	v_pk_mul_f32 v[60:61], v[34:35], v[60:61]
	v_sub_f32_e32 v62, v62, v63
	v_add_f32_e32 v60, v61, v60
	v_add_f32_e32 v60, v60, v85
	v_add_f32_e32 v62, v62, v89
	v_cndmask_b32_e64 v85, v85, v60, s[6:7]
	v_cndmask_b32_e64 v61, v83, v94, s[6:7]
	v_cndmask_b32_e64 v60, v82, v78, s[6:7]
	v_cndmask_b32_e64 v67, v89, v62, s[6:7]
	v_cndmask_b32_e64 v66, v88, v66, s[6:7]
	v_cndmask_b32_e64 v63, v87, v79, s[6:7]
	v_cndmask_b32_e64 v62, v86, v81, s[6:7]
	v_mov_b32_dpp v86, v60 row_shr:1 row_mask:0xf bank_mask:0xf bound_ctrl:1
	v_mov_b32_dpp v87, v61 row_shr:1 row_mask:0xf bank_mask:0xf bound_ctrl:1
	v_mov_b32_e32 v88, v90
	v_mov_b32_e32 v89, v92
	v_mov_b32_dpp v82, v62 row_shr:1 row_mask:0xf bank_mask:0xf bound_ctrl:1
	v_mov_b32_dpp v83, v63 row_shr:1 row_mask:0xf bank_mask:0xf bound_ctrl:1
	v_pk_mul_f32 v[94:95], v[88:89], v[86:87]
	v_pk_mul_f32 v[92:93], v[92:93], v[92:93]
	v_pk_fma_f32 v[94:95], v[96:97], v[82:83], v[94:95]
	v_pk_mul_f32 v[90:91], v[90:91], v[90:91]
	v_pk_add_f32 v[60:61], v[94:95], v[60:61]
	v_mov_b32_e32 v94, v90
	v_mov_b32_e32 v95, v92
	v_mov_b32_e32 v92, v91
	v_pk_mul_f32 v[86:87], v[96:97], v[86:87]
	v_pk_add_f32 v[90:91], v[94:95], v[92:93] neg_lo:[0,1] neg_hi:[0,1]
	v_pk_add_f32 v[92:93], v[88:89], v[88:89]
	v_pk_fma_f32 v[82:83], v[88:89], v[82:83], v[86:87] neg_lo:[0,0,1] neg_hi:[0,0,1]
	v_pk_mul_f32 v[92:93], v[96:97], v[92:93]
	v_mov_b32_dpp v94, v60 row_shr:2 row_mask:0xf bank_mask:0xf bound_ctrl:1
	v_mov_b32_dpp v95, v61 row_shr:2 row_mask:0xf bank_mask:0xf bound_ctrl:1
	v_pk_add_f32 v[62:63], v[82:83], v[62:63]
	v_pk_mul_f32 v[98:99], v[90:91], v[94:95]
	v_pk_mul_f32 v[86:87], v[92:93], v[94:95]
	v_mov_b32_dpp v82, v62 row_shr:2 row_mask:0xf bank_mask:0xf bound_ctrl:1
; #define SSM_SCAN_STEP(D, SQ) { _Pragma("unroll") for (int r = 0; r < 4; ++r) { \
;                     const float sr = dppf<DPP_SHR(D)>(Er[r]), si = dppf<DPP_SHR(D)>(Ei[r]); \
;                     Er[r] += mr[r] * sr - mi[r] * si; Ei[r] += mr[r] * si + mi[r] * sr; \
;                     if (SQ) { const float nr = mr[r] * mr[r] - mi[r] * mi[r], ni = 2.f * mr[r] * mi[r]; mr[r] = nr; mi[r] = ni; } } }
; template <bool PASS2>
; __device__ __forceinline__ void ssm_phase(const Params& p, const Frame& F0) {
;     ...
;             for (int i = 0; i < 4; ++i) {
;                 __builtin_amdgcn_sched_barrier(0);
;                 f32x4 Er = (f32x4){0.f, 0.f, 0.f, 0.f}, Ei = Er;
; #pragma unroll
;                 for (int ks = 0; ks < 4; ++ks) { Er = __builtin_amdgcn_mfma_f32_16x16x32_bf16(frag[(i * 4 + ks) * 64], uf[ks], Er, 0, 0, 0);
;                                                  Ei = __builtin_amdgcn_mfma_f32_16x16x32_bf16(frag[((i + 4) * 4 + ks) * 64], uf[ks], Ei, 0, 0, 0); }
;                 const f32x4 ma = m1t[8 * i], mb = m1t[8 * i + 1];
;                 float mr[4] = {ma[0], ma[2], mb[0], mb[2]}, mi[4] = {ma[1], ma[3], mb[1], mb[3]};
;                 float hr[4], hi[4];
; #pragma unroll
;                 for (int r = 0; r < 4; ++r) { hr[r] = dppf<DPP_ROR(1)>(xs[i][r]); hi[r] = dppf<DPP_ROR(1)>(xs[i + 4][r]);
;                     if (j == 0) { Er[r] += mr[r] * hr[r] - mi[r] * hi[r]; Ei[r] += mr[r] * hi[r] + mi[r] * hr[r]; } }
;     ...
;                 SSM_SCAN_STEP(1, 1) SSM_SCAN_STEP(2, 1) SSM_SCAN_STEP(4, 1) SSM_SCAN_STEP(8, 0)
	v_mov_b32_dpp v83, v63 row_shr:2 row_mask:0xf bank_mask:0xf bound_ctrl:1
	v_pk_fma_f32 v[86:87], v[90:91], v[82:83], v[86:87] neg_lo:[0,0,1] neg_hi:[0,0,1]
	v_pk_fma_f32 v[82:83], v[92:93], v[82:83], v[98:99]
	v_pk_mul_f32 v[100:101], v[92:93], v[92:93]
	v_pk_add_f32 v[102:103], v[90:91], v[90:91]
	v_pk_add_f32 v[60:61], v[60:61], v[82:83]
	v_pk_fma_f32 v[100:101], v[90:91], v[90:91], v[100:101] neg_lo:[0,0,1] neg_hi:[0,0,1]
	v_pk_mul_f32 v[102:103], v[92:93], v[102:103]
	v_pk_add_f32 v[62:63], v[86:87], v[62:63]
	v_mov_b32_dpp v86, v60 row_shr:4 row_mask:0xf bank_mask:0xf bound_ctrl:1
	v_mov_b32_dpp v87, v61 row_shr:4 row_mask:0xf bank_mask:0xf bound_ctrl:1
	v_mov_b32_dpp v82, v62 row_shr:4 row_mask:0xf bank_mask:0xf bound_ctrl:1
	v_mov_b32_dpp v83, v63 row_shr:4 row_mask:0xf bank_mask:0xf bound_ctrl:1
	v_pk_mul_f32 v[88:89], v[102:103], v[86:87]
	v_pk_mul_f32 v[86:87], v[100:101], v[86:87]
	v_pk_fma_f32 v[88:89], v[100:101], v[82:83], v[88:89] neg_lo:[0,0,1] neg_hi:[0,0,1]
	v_pk_fma_f32 v[82:83], v[102:103], v[82:83], v[86:87]
	v_pk_mul_f32 v[110:111], v[102:103], v[102:103]
	v_pk_add_f32 v[112:113], v[100:101], v[100:101]
	v_pk_add_f32 v[60:61], v[60:61], v[82:83]
	v_pk_fma_f32 v[110:111], v[100:101], v[100:101], v[110:111] neg_lo:[0,0,1] neg_hi:[0,0,1]
	v_pk_mul_f32 v[112:113], v[102:103], v[112:113]
	v_pk_add_f32 v[62:63], v[62:63], v[88:89]
	v_mov_b32_dpp v86, v60 row_shr:8 row_mask:0xf bank_mask:0xf bound_ctrl:1
	v_mov_b32_dpp v87, v61 row_shr:8 row_mask:0xf bank_mask:0xf bound_ctrl:1
	v_mov_b32_dpp v82, v62 row_shr:8 row_mask:0xf bank_mask:0xf bound_ctrl:1
	v_mov_b32_dpp v83, v63 row_shr:8 row_mask:0xf bank_mask:0xf bound_ctrl:1
	v_pk_mul_f32 v[88:89], v[112:113], v[86:87]
	v_pk_mul_f32 v[86:87], v[110:111], v[86:87]
	v_cndmask_b32_e64 v84, v84, v68, s[6:7]
	v_pk_fma_f32 v[88:89], v[110:111], v[82:83], v[88:89] neg_lo:[0,0,1] neg_hi:[0,0,1]
	v_pk_fma_f32 v[82:83], v[112:113], v[82:83], v[86:87]
	v_mov_b32_dpp v78, v84 row_shr:1 row_mask:0xf bank_mask:0xf bound_ctrl:1
	v_mov_b32_dpp v79, v85 row_shr:1 row_mask:0xf bank_mask:0xf bound_ctrl:1
	v_pk_add_f32 v[60:61], v[60:61], v[82:83]
	v_mov_b32_e32 v82, v32
	v_mov_b32_e32 v83, v34
	v_mov_b32_dpp v68, v66 row_shr:1 row_mask:0xf bank_mask:0xf bound_ctrl:1
	v_mov_b32_dpp v69, v67 row_shr:1 row_mask:0xf bank_mask:0xf bound_ctrl:1
	v_pk_add_f32 v[62:63], v[62:63], v[88:89]
	v_pk_mul_f32 v[86:87], v[82:83], v[78:79]
	v_mov_b32_e32 v88, v33
	v_mov_b32_e32 v89, v35
	v_pk_fma_f32 v[86:87], v[88:89], v[68:69], v[86:87]
	v_pk_mul_f32 v[34:35], v[34:35], v[34:35]
	v_pk_mul_f32 v[32:33], v[32:33], v[32:33]
	v_pk_mul_f32 v[78:79], v[88:89], v[78:79]
	v_pk_add_f32 v[84:85], v[86:87], v[84:85]
	v_mov_b32_e32 v86, v32
	v_mov_b32_e32 v87, v34
	v_mov_b32_e32 v34, v33
	v_pk_fma_f32 v[68:69], v[82:83], v[68:69], v[78:79] neg_lo:[0,0,1] neg_hi:[0,0,1]
	v_pk_add_f32 v[32:33], v[86:87], v[34:35] neg_lo:[0,1] neg_hi:[0,1]
	v_pk_add_f32 v[34:35], v[82:83], v[82:83]
	v_mov_b32_dpp v86, v84 row_shr:2 row_mask:0xf bank_mask:0xf bound_ctrl:1
	v_mov_b32_dpp v87, v85 row_shr:2 row_mask:0xf bank_mask:0xf bound_ctrl:1
	v_pk_add_f32 v[66:67], v[68:69], v[66:67]
	v_pk_mul_f32 v[34:35], v[88:89], v[34:35]
	v_pk_mul_f32 v[90:91], v[32:33], v[86:87]
	v_pk_add_f32 v[94:95], v[32:33], v[32:33]
	v_mov_b32_dpp v68, v66 row_shr:2 row_mask:0xf bank_mask:0xf bound_ctrl:1
	v_mov_b32_dpp v69, v67 row_shr:2 row_mask:0xf bank_mask:0xf bound_ctrl:1
	v_pk_mul_f32 v[92:93], v[34:35], v[34:35]
	v_pk_mul_f32 v[94:95], v[34:35], v[94:95]
	v_pk_mul_f32 v[78:79], v[34:35], v[86:87]
	v_pk_fma_f32 v[34:35], v[34:35], v[68:69], v[90:91]
	v_pk_fma_f32 v[92:93], v[32:33], v[32:33], v[92:93] neg_lo:[0,0,1] neg_hi:[0,0,1]
	v_pk_fma_f32 v[32:33], v[32:33], v[68:69], v[78:79] neg_lo:[0,0,1] neg_hi:[0,0,1]
	v_pk_add_f32 v[34:35], v[84:85], v[34:35]
	v_pk_add_f32 v[32:33], v[66:67], v[32:33]
	v_pk_add_f32 v[98:99], v[92:93], v[92:93]
	v_mov_b32_dpp v68, v34 row_shr:4 row_mask:0xf bank_mask:0xf bound_ctrl:1
	v_mov_b32_dpp v69, v35 row_shr:4 row_mask:0xf bank_mask:0xf bound_ctrl:1
	v_mov_b32_dpp v66, v32 row_shr:4 row_mask:0xf bank_mask:0xf bound_ctrl:1
	v_mov_b32_dpp v67, v33 row_shr:4 row_mask:0xf bank_mask:0xf bound_ctrl:1
	v_pk_mul_f32 v[78:79], v[94:95], v[68:69]
	v_pk_mul_f32 v[68:69], v[92:93], v[68:69]
	v_pk_fma_f32 v[78:79], v[92:93], v[66:67], v[78:79] neg_lo:[0,0,1] neg_hi:[0,0,1]
	v_pk_fma_f32 v[66:67], v[94:95], v[66:67], v[68:69]
	v_pk_mul_f32 v[96:97], v[94:95], v[94:95]
	v_pk_add_f32 v[34:35], v[34:35], v[66:67]
	v_pk_mul_f32 v[98:99], v[94:95], v[98:99]
	v_pk_add_f32 v[32:33], v[32:33], v[78:79]
	v_mov_b32_dpp v78, v34 row_shr:8 row_mask:0xf bank_mask:0xf bound_ctrl:1
	v_mov_b32_dpp v79, v35 row_shr:8 row_mask:0xf bank_mask:0xf bound_ctrl:1
	v_pk_fma_f32 v[96:97], v[92:93], v[92:93], v[96:97] neg_lo:[0,0,1] neg_hi:[0,0,1]
	v_mov_b32_dpp v66, v32 row_shr:8 row_mask:0xf bank_mask:0xf bound_ctrl:1
	v_mov_b32_dpp v67, v33 row_shr:8 row_mask:0xf bank_mask:0xf bound_ctrl:1
	v_pk_mul_f32 v[68:69], v[98:99], v[78:79]
	s_nop 0
	v_pk_fma_f32 v[68:69], v[96:97], v[66:67], v[68:69] neg_lo:[0,0,1] neg_hi:[0,0,1]
	s_nop 0
	v_pk_add_f32 v[68:69], v[32:33], v[68:69]
	v_pk_mul_f32 v[32:33], v[96:97], v[78:79]
	s_nop 0
	v_pk_fma_f32 v[32:33], v[98:99], v[66:67], v[32:33]
	s_nop 0
	v_pk_add_f32 v[66:67], v[34:35], v[32:33]
	v_mov_b32_dpp v79, v54 row_ror:1 row_mask:0xf bank_mask:0xf bound_ctrl:1
	v_mov_b32_dpp v78, v52 row_ror:1 row_mask:0xf bank_mask:0xf bound_ctrl:1
	v_mov_b32_dpp v55, v55 row_ror:1 row_mask:0xf bank_mask:0xf bound_ctrl:1
	v_mov_b32_dpp v54, v53 row_ror:1 row_mask:0xf bank_mask:0xf bound_ctrl:1
	v_mfma_f32_16x16x32_bf16 v[32:35], v[162:165], v[28:31], 0
	v_mfma_f32_16x16x32_bf16 v[32:35], v[166:169], v[24:27], v[32:35]
	v_mfma_f32_16x16x32_bf16 v[82:85], v[228:231], v[28:31], 0
	v_mfma_f32_16x16x32_bf16 v[82:85], v[232:235], v[24:27], v[82:85]
	v_mfma_f32_16x16x32_bf16 v[32:35], v[170:173], v[20:23], v[32:35]
	v_mfma_f32_16x16x32_bf16 v[82:85], v[236:239], v[20:23], v[82:85]
	v_mfma_f32_16x16x32_bf16 v[86:89], v[174:177], v[16:19], v[32:35]
	s_nop 2
	v_mfma_f32_16x16x32_bf16 v[82:85], v[240:243], v[16:19], v[82:85]
	ds_read_b128 v[90:93], v109 offset:256
	s_nop 0
	ds_read_b128 v[32:35], v109 offset:272
	s_waitcnt lgkmcnt(1)
; #define SSM_SCAN_STEP(D, SQ) { _Pragma("unroll") for (int r = 0; r < 4; ++r) { \
;                     const float sr = dppf<DPP_SHR(D)>(Er[r]), si = dppf<DPP_SHR(D)>(Ei[r]); \
;                     Er[r] += mr[r] * sr - mi[r] * si; Ei[r] += mr[r] * si + mi[r] * sr; \
;                     if (SQ) { const float nr = mr[r] * mr[r] - mi[r] * mi[r], ni = 2.f * mr[r] * mi[r]; mr[r] = nr; mi[r] = ni; } } }
; template <bool PASS2>
; __device__ __forceinline__ void ssm_phase(const Params& p, const Frame& F0) {
;     ...
;                 const f32x4 ma = m1t[8 * i], mb = m1t[8 * i + 1];
;                 float mr[4] = {ma[0], ma[2], mb[0], mb[2]}, mi[4] = {ma[1], ma[3], mb[1], mb[3]};
;                 float hr[4], hi[4];
; #pragma unroll
;                 for (int r = 0; r < 4; ++r) { hr[r] = dppf<DPP_ROR(1)>(xs[i][r]); hi[r] = dppf<DPP_ROR(1)>(xs[i + 4][r]);
;                     if (j == 0) { Er[r] += mr[r] * hr[r] - mi[r] * hi[r]; Ei[r] += mr[r] * hi[r] + mi[r] * hr[r]; } }
;     ...
;                 SSM_SCAN_STEP(1, 1) SSM_SCAN_STEP(2, 1) SSM_SCAN_STEP(4, 1) SSM_SCAN_STEP(8, 0)
	v_pk_mul_f32 v[94:95], v[90:91], v[78:79] op_sel:[0,1] op_sel_hi:[1,0]
	s_nop 0
	v_sub_f32_e32 v52, v94, v95
	v_pk_mul_f32 v[78:79], v[90:91], v[78:79]
	v_add_f32_e32 v81, v86, v52
	v_add_f32_e32 v52, v79, v78
	v_add_f32_e32 v78, v82, v52
	v_pk_mul_f32 v[52:53], v[92:93], v[54:55] op_sel:[0,1] op_sel_hi:[1,0]
	v_mov_b32_e32 v96, v91
	v_sub_f32_e32 v52, v52, v53
	v_add_f32_e32 v79, v52, v87
	v_pk_mul_f32 v[52:53], v[92:93], v[54:55]
	v_mov_b32_e32 v97, v93
	v_add_f32_e32 v52, v53, v52
	v_add_f32_e32 v94, v52, v83
	v_mov_b32_dpp v53, v58 row_ror:1 row_mask:0xf bank_mask:0xf bound_ctrl:1
	v_mov_b32_dpp v52, v56 row_ror:1 row_mask:0xf bank_mask:0xf bound_ctrl:1
	s_waitcnt lgkmcnt(0)
	v_pk_mul_f32 v[54:55], v[32:33], v[52:53] op_sel:[0,1] op_sel_hi:[1,0]
	v_pk_mul_f32 v[52:53], v[32:33], v[52:53]
	v_sub_f32_e32 v54, v54, v55
	v_add_f32_e32 v52, v53, v52
	v_add_f32_e32 v58, v52, v84
	v_mov_b32_dpp v53, v59 row_ror:1 row_mask:0xf bank_mask:0xf bound_ctrl:1
	v_mov_b32_dpp v52, v57 row_ror:1 row_mask:0xf bank_mask:0xf bound_ctrl:1
	v_add_f32_e32 v56, v54, v88
	v_pk_mul_f32 v[54:55], v[34:35], v[52:53] op_sel:[0,1] op_sel_hi:[1,0]
	v_pk_mul_f32 v[52:53], v[34:35], v[52:53]
	v_sub_f32_e32 v54, v54, v55
	v_add_f32_e32 v52, v53, v52
	v_add_f32_e32 v52, v52, v85
	v_add_f32_e32 v54, v54, v89
	v_cndmask_b32_e64 v85, v85, v52, s[6:7]
	v_cndmask_b32_e64 v53, v83, v94, s[6:7]
	v_cndmask_b32_e64 v52, v82, v78, s[6:7]
	v_cndmask_b32_e64 v57, v89, v54, s[6:7]
	v_cndmask_b32_e64 v56, v88, v56, s[6:7]
	v_cndmask_b32_e64 v55, v87, v79, s[6:7]
	v_cndmask_b32_e64 v54, v86, v81, s[6:7]
	v_mov_b32_dpp v86, v52 row_shr:1 row_mask:0xf bank_mask:0xf bound_ctrl:1
	v_mov_b32_dpp v87, v53 row_shr:1 row_mask:0xf bank_mask:0xf bound_ctrl:1
	v_mov_b32_e32 v88, v90
	v_mov_b32_e32 v89, v92
	v_mov_b32_dpp v82, v54 row_shr:1 row_mask:0xf bank_mask:0xf bound_ctrl:1
	v_mov_b32_dpp v83, v55 row_shr:1 row_mask:0xf bank_mask:0xf bound_ctrl:1
	v_pk_mul_f32 v[94:95], v[88:89], v[86:87]
	v_pk_mul_f32 v[92:93], v[92:93], v[92:93]
	v_pk_fma_f32 v[94:95], v[96:97], v[82:83], v[94:95]
	v_pk_mul_f32 v[90:91], v[90:91], v[90:91]
	v_pk_add_f32 v[52:53], v[94:95], v[52:53]
	v_mov_b32_e32 v94, v90
	v_mov_b32_e32 v95, v92
	v_mov_b32_e32 v92, v91
	v_pk_mul_f32 v[86:87], v[96:97], v[86:87]
	v_pk_add_f32 v[90:91], v[94:95], v[92:93] neg_lo:[0,1] neg_hi:[0,1]
	v_pk_add_f32 v[92:93], v[88:89], v[88:89]
	v_pk_fma_f32 v[82:83], v[88:89], v[82:83], v[86:87] neg_lo:[0,0,1] neg_hi:[0,0,1]
	v_pk_mul_f32 v[92:93], v[96:97], v[92:93]
	v_mov_b32_dpp v94, v52 row_shr:2 row_mask:0xf bank_mask:0xf bound_ctrl:1
	v_mov_b32_dpp v95, v53 row_shr:2 row_mask:0xf bank_mask:0xf bound_ctrl:1
	v_pk_add_f32 v[54:55], v[82:83], v[54:55]
	v_pk_mul_f32 v[98:99], v[90:91], v[94:95]
	v_pk_mul_f32 v[86:87], v[92:93], v[94:95]
	v_mov_b32_dpp v82, v54 row_shr:2 row_mask:0xf bank_mask:0xf bound_ctrl:1
	v_mov_b32_dpp v83, v55 row_shr:2 row_mask:0xf bank_mask:0xf bound_ctrl:1
	v_pk_fma_f32 v[86:87], v[90:91], v[82:83], v[86:87] neg_lo:[0,0,1] neg_hi:[0,0,1]
	v_pk_fma_f32 v[82:83], v[92:93], v[82:83], v[98:99]
	v_pk_mul_f32 v[100:101], v[92:93], v[92:93]
	v_pk_add_f32 v[102:103], v[90:91], v[90:91]
	v_pk_add_f32 v[52:53], v[52:53], v[82:83]
	v_pk_fma_f32 v[100:101], v[90:91], v[90:91], v[100:101] neg_lo:[0,0,1] neg_hi:[0,0,1]
	v_pk_mul_f32 v[102:103], v[92:93], v[102:103]
	v_pk_add_f32 v[54:55], v[86:87], v[54:55]
	v_mov_b32_dpp v86, v52 row_shr:4 row_mask:0xf bank_mask:0xf bound_ctrl:1
	v_mov_b32_dpp v87, v53 row_shr:4 row_mask:0xf bank_mask:0xf bound_ctrl:1
	v_mov_b32_dpp v82, v54 row_shr:4 row_mask:0xf bank_mask:0xf bound_ctrl:1
	v_mov_b32_dpp v83, v55 row_shr:4 row_mask:0xf bank_mask:0xf bound_ctrl:1
	v_pk_mul_f32 v[88:89], v[102:103], v[86:87]
	v_pk_mul_f32 v[86:87], v[100:101], v[86:87]
	v_pk_fma_f32 v[88:89], v[100:101], v[82:83], v[88:89] neg_lo:[0,0,1] neg_hi:[0,0,1]
	v_pk_fma_f32 v[82:83], v[102:103], v[82:83], v[86:87]
	v_pk_mul_f32 v[110:111], v[102:103], v[102:103]
	v_pk_add_f32 v[112:113], v[100:101], v[100:101]
	v_pk_add_f32 v[52:53], v[52:53], v[82:83]
	v_pk_fma_f32 v[110:111], v[100:101], v[100:101], v[110:111] neg_lo:[0,0,1] neg_hi:[0,0,1]
	v_pk_mul_f32 v[112:113], v[102:103], v[112:113]
	v_pk_add_f32 v[54:55], v[54:55], v[88:89]
	v_mov_b32_dpp v86, v52 row_shr:8 row_mask:0xf bank_mask:0xf bound_ctrl:1
	v_mov_b32_dpp v87, v53 row_shr:8 row_mask:0xf bank_mask:0xf bound_ctrl:1
	v_mov_b32_dpp v82, v54 row_shr:8 row_mask:0xf bank_mask:0xf bound_ctrl:1
	v_mov_b32_dpp v83, v55 row_shr:8 row_mask:0xf bank_mask:0xf bound_ctrl:1
	v_pk_mul_f32 v[88:89], v[112:113], v[86:87]
	v_pk_mul_f32 v[86:87], v[110:111], v[86:87]
	v_cndmask_b32_e64 v84, v84, v58, s[6:7]
	v_pk_fma_f32 v[88:89], v[110:111], v[82:83], v[88:89] neg_lo:[0,0,1] neg_hi:[0,0,1]
	v_pk_fma_f32 v[82:83], v[112:113], v[82:83], v[86:87]
	v_mov_b32_dpp v78, v84 row_shr:1 row_mask:0xf bank_mask:0xf bound_ctrl:1
	v_mov_b32_dpp v79, v85 row_shr:1 row_mask:0xf bank_mask:0xf bound_ctrl:1
	v_pk_add_f32 v[52:53], v[52:53], v[82:83]
	v_mov_b32_e32 v82, v32
	v_mov_b32_e32 v83, v34
	v_mov_b32_dpp v58, v56 row_shr:1 row_mask:0xf bank_mask:0xf bound_ctrl:1
	v_mov_b32_dpp v59, v57 row_shr:1 row_mask:0xf bank_mask:0xf bound_ctrl:1
	v_pk_add_f32 v[54:55], v[54:55], v[88:89]
	v_pk_mul_f32 v[86:87], v[82:83], v[78:79]
	v_mov_b32_e32 v88, v33
	v_mov_b32_e32 v89, v35
	v_pk_fma_f32 v[86:87], v[88:89], v[58:59], v[86:87]
	v_pk_mul_f32 v[34:35], v[34:35], v[34:35]
	v_pk_mul_f32 v[32:33], v[32:33], v[32:33]
	v_pk_mul_f32 v[78:79], v[88:89], v[78:79]
	v_pk_add_f32 v[84:85], v[86:87], v[84:85]
	v_mov_b32_e32 v86, v32
	v_mov_b32_e32 v87, v34
	v_mov_b32_e32 v34, v33
; #define SSM_SCAN_STEP(D, SQ) { _Pragma("unroll") for (int r = 0; r < 4; ++r) { \
;                     const float sr = dppf<DPP_SHR(D)>(Er[r]), si = dppf<DPP_SHR(D)>(Ei[r]); \
;                     Er[r] += mr[r] * sr - mi[r] * si; Ei[r] += mr[r] * si + mi[r] * sr; \
;                     if (SQ) { const float nr = mr[r] * mr[r] - mi[r] * mi[r], ni = 2.f * mr[r] * mi[r]; mr[r] = nr; mi[r] = ni; } } }
; template <bool PASS2>
; __device__ __forceinline__ void ssm_phase(const Params& p, const Frame& F0) {
;     ...
;             for (int i = 0; i < 4; ++i) {
;                 __builtin_amdgcn_sched_barrier(0);
;                 f32x4 Er = (f32x4){0.f, 0.f, 0.f, 0.f}, Ei = Er;
; #pragma unroll
;                 for (int ks = 0; ks < 4; ++ks) { Er = __builtin_amdgcn_mfma_f32_16x16x32_bf16(frag[(i * 4 + ks) * 64], uf[ks], Er, 0, 0, 0);
;                                                  Ei = __builtin_amdgcn_mfma_f32_16x16x32_bf16(frag[((i + 4) * 4 + ks) * 64], uf[ks], Ei, 0, 0, 0); }
;                 const f32x4 ma = m1t[8 * i], mb = m1t[8 * i + 1];
;                 float mr[4] = {ma[0], ma[2], mb[0], mb[2]}, mi[4] = {ma[1], ma[3], mb[1], mb[3]};
;                 float hr[4], hi[4];
; #pragma unroll
;                 for (int r = 0; r < 4; ++r) { hr[r] = dppf<DPP_ROR(1)>(xs[i][r]); hi[r] = dppf<DPP_ROR(1)>(xs[i + 4][r]);
;                     if (j == 0) { Er[r] += mr[r] * hr[r] - mi[r] * hi[r]; Ei[r] += mr[r] * hi[r] + mi[r] * hr[r]; } }
;     ...
;                 SSM_SCAN_STEP(1, 1) SSM_SCAN_STEP(2, 1) SSM_SCAN_STEP(4, 1) SSM_SCAN_STEP(8, 0)
	v_pk_fma_f32 v[58:59], v[82:83], v[58:59], v[78:79] neg_lo:[0,0,1] neg_hi:[0,0,1]
	v_pk_add_f32 v[32:33], v[86:87], v[34:35] neg_lo:[0,1] neg_hi:[0,1]
	v_pk_add_f32 v[34:35], v[82:83], v[82:83]
	v_mov_b32_dpp v86, v84 row_shr:2 row_mask:0xf bank_mask:0xf bound_ctrl:1
	v_mov_b32_dpp v87, v85 row_shr:2 row_mask:0xf bank_mask:0xf bound_ctrl:1
	v_pk_add_f32 v[56:57], v[58:59], v[56:57]
	v_pk_mul_f32 v[34:35], v[88:89], v[34:35]
	v_pk_mul_f32 v[90:91], v[32:33], v[86:87]
	v_pk_add_f32 v[94:95], v[32:33], v[32:33]
	v_mov_b32_dpp v58, v56 row_shr:2 row_mask:0xf bank_mask:0xf bound_ctrl:1
	v_mov_b32_dpp v59, v57 row_shr:2 row_mask:0xf bank_mask:0xf bound_ctrl:1
	v_pk_mul_f32 v[92:93], v[34:35], v[34:35]
	v_pk_mul_f32 v[94:95], v[34:35], v[94:95]
	v_pk_mul_f32 v[78:79], v[34:35], v[86:87]
	v_pk_fma_f32 v[34:35], v[34:35], v[58:59], v[90:91]
	v_pk_fma_f32 v[92:93], v[32:33], v[32:33], v[92:93] neg_lo:[0,0,1] neg_hi:[0,0,1]
	v_pk_fma_f32 v[32:33], v[32:33], v[58:59], v[78:79] neg_lo:[0,0,1] neg_hi:[0,0,1]
	v_pk_add_f32 v[34:35], v[84:85], v[34:35]
	v_pk_add_f32 v[32:33], v[56:57], v[32:33]
	v_pk_add_f32 v[98:99], v[92:93], v[92:93]
	v_mov_b32_dpp v58, v34 row_shr:4 row_mask:0xf bank_mask:0xf bound_ctrl:1
	v_mov_b32_dpp v59, v35 row_shr:4 row_mask:0xf bank_mask:0xf bound_ctrl:1
	v_mov_b32_dpp v56, v32 row_shr:4 row_mask:0xf bank_mask:0xf bound_ctrl:1
	v_mov_b32_dpp v57, v33 row_shr:4 row_mask:0xf bank_mask:0xf bound_ctrl:1
	v_pk_mul_f32 v[78:79], v[94:95], v[58:59]
	v_pk_mul_f32 v[58:59], v[92:93], v[58:59]
	v_pk_fma_f32 v[78:79], v[92:93], v[56:57], v[78:79] neg_lo:[0,0,1] neg_hi:[0,0,1]
	v_pk_fma_f32 v[56:57], v[94:95], v[56:57], v[58:59]
	v_pk_mul_f32 v[96:97], v[94:95], v[94:95]
	v_pk_add_f32 v[34:35], v[34:35], v[56:57]
	v_pk_mul_f32 v[98:99], v[94:95], v[98:99]
	v_pk_add_f32 v[32:33], v[32:33], v[78:79]
	v_mov_b32_dpp v78, v34 row_shr:8 row_mask:0xf bank_mask:0xf bound_ctrl:1
	v_mov_b32_dpp v79, v35 row_shr:8 row_mask:0xf bank_mask:0xf bound_ctrl:1
	v_pk_fma_f32 v[96:97], v[92:93], v[92:93], v[96:97] neg_lo:[0,0,1] neg_hi:[0,0,1]
	v_mov_b32_dpp v56, v32 row_shr:8 row_mask:0xf bank_mask:0xf bound_ctrl:1
	v_mov_b32_dpp v57, v33 row_shr:8 row_mask:0xf bank_mask:0xf bound_ctrl:1
	v_pk_mul_f32 v[58:59], v[98:99], v[78:79]
	s_nop 0
	v_pk_fma_f32 v[58:59], v[96:97], v[56:57], v[58:59] neg_lo:[0,0,1] neg_hi:[0,0,1]
	s_nop 0
	v_pk_add_f32 v[58:59], v[32:33], v[58:59]
	v_pk_mul_f32 v[32:33], v[96:97], v[78:79]
	s_nop 0
	v_pk_fma_f32 v[32:33], v[98:99], v[56:57], v[32:33]
	s_nop 0
	v_pk_add_f32 v[56:57], v[34:35], v[32:33]
	v_mfma_f32_16x16x32_bf16 v[32:35], v[178:181], v[28:31], 0
	v_mfma_f32_16x16x32_bf16 v[28:31], v[244:247], v[28:31], 0
	v_mfma_f32_16x16x32_bf16 v[32:35], v[182:185], v[24:27], v[32:35]
	v_mfma_f32_16x16x32_bf16 v[24:27], v[248:251], v[24:27], v[28:31]
	s_nop 2
	v_mfma_f32_16x16x32_bf16 v[28:31], v[186:189], v[20:23], v[32:35]
	s_nop 2
	ds_read_b128 v[32:35], v105 offset:30720
	s_waitcnt lgkmcnt(0)
	v_mfma_f32_16x16x32_bf16 v[20:23], v[32:35], v[20:23], v[24:27]
	s_nop 2
	v_mov_b32_dpp v33, v46 row_ror:1 row_mask:0xf bank_mask:0xf bound_ctrl:1
	v_mov_b32_dpp v32, v44 row_ror:1 row_mask:0xf bank_mask:0xf bound_ctrl:1
	v_mfma_f32_16x16x32_bf16 v[24:27], v[190:193], v[16:19], v[28:31]
	s_nop 2
	ds_read_b128 v[28:31], v105 offset:31744
	s_waitcnt lgkmcnt(0)
	v_mfma_f32_16x16x32_bf16 v[20:23], v[28:31], v[16:19], v[20:23]
	ds_read_b128 v[28:31], v109 offset:384
	ds_read_b128 v[16:19], v109 offset:400
	s_waitcnt lgkmcnt(1)
	v_pk_mul_f32 v[34:35], v[28:29], v[32:33] op_sel:[0,1] op_sel_hi:[1,0]
	v_pk_mul_f32 v[32:33], v[28:29], v[32:33]
	v_sub_f32_e32 v34, v34, v35
	v_add_f32_e32 v32, v33, v32
	s_nop 0
	v_add_f32_e32 v46, v20, v32
	v_mov_b32_dpp v33, v47 row_ror:1 row_mask:0xf bank_mask:0xf bound_ctrl:1
	v_mov_b32_dpp v32, v45 row_ror:1 row_mask:0xf bank_mask:0xf bound_ctrl:1
	v_add_f32_e32 v44, v24, v34
	v_pk_mul_f32 v[34:35], v[30:31], v[32:33] op_sel:[0,1] op_sel_hi:[1,0]
	v_pk_mul_f32 v[32:33], v[30:31], v[32:33]
	v_sub_f32_e32 v34, v34, v35
	v_add_f32_e32 v32, v33, v32
	v_add_f32_e32 v47, v32, v21
	v_mov_b32_dpp v33, v50 row_ror:1 row_mask:0xf bank_mask:0xf bound_ctrl:1
	v_mov_b32_dpp v32, v48 row_ror:1 row_mask:0xf bank_mask:0xf bound_ctrl:1
	v_add_f32_e32 v45, v34, v25
	s_waitcnt lgkmcnt(0)
; #define SSM_SCAN_STEP(D, SQ) { _Pragma("unroll") for (int r = 0; r < 4; ++r) { \
;                     const float sr = dppf<DPP_SHR(D)>(Er[r]), si = dppf<DPP_SHR(D)>(Ei[r]); \
;                     Er[r] += mr[r] * sr - mi[r] * si; Ei[r] += mr[r] * si + mi[r] * sr; \
;                     if (SQ) { const float nr = mr[r] * mr[r] - mi[r] * mi[r], ni = 2.f * mr[r] * mi[r]; mr[r] = nr; mi[r] = ni; } } }
; template <bool PASS2>
; __device__ __forceinline__ void ssm_phase(const Params& p, const Frame& F0) {
;     ...
;                 const f32x4 ma = m1t[8 * i], mb = m1t[8 * i + 1];
;                 float mr[4] = {ma[0], ma[2], mb[0], mb[2]}, mi[4] = {ma[1], ma[3], mb[1], mb[3]};
;                 float hr[4], hi[4];
; #pragma unroll
;                 for (int r = 0; r < 4; ++r) { hr[r] = dppf<DPP_ROR(1)>(xs[i][r]); hi[r] = dppf<DPP_ROR(1)>(xs[i + 4][r]);
;                     if (j == 0) { Er[r] += mr[r] * hr[r] - mi[r] * hi[r]; Ei[r] += mr[r] * hi[r] + mi[r] * hr[r]; } }
;     ...
;                 SSM_SCAN_STEP(1, 1) SSM_SCAN_STEP(2, 1) SSM_SCAN_STEP(4, 1) SSM_SCAN_STEP(8, 0)
	v_pk_mul_f32 v[34:35], v[16:17], v[32:33] op_sel:[0,1] op_sel_hi:[1,0]
	v_pk_mul_f32 v[32:33], v[16:17], v[32:33]
	v_sub_f32_e32 v34, v34, v35
	v_add_f32_e32 v32, v33, v32
	v_add_f32_e32 v50, v32, v22
	v_mov_b32_dpp v33, v51 row_ror:1 row_mask:0xf bank_mask:0xf bound_ctrl:1
	v_mov_b32_dpp v32, v49 row_ror:1 row_mask:0xf bank_mask:0xf bound_ctrl:1
	v_add_f32_e32 v48, v34, v26
	v_pk_mul_f32 v[34:35], v[18:19], v[32:33] op_sel:[0,1] op_sel_hi:[1,0]
	v_pk_mul_f32 v[32:33], v[18:19], v[32:33]
	v_sub_f32_e32 v34, v34, v35
	v_add_f32_e32 v49, v34, v27
	v_add_f32_e32 v32, v33, v32
	v_cndmask_b32_e64 v35, v21, v47, s[6:7]
	v_cndmask_b32_e64 v34, v20, v46, s[6:7]
	v_add_f32_e32 v32, v32, v23
	v_cndmask_b32_e64 v21, v27, v49, s[6:7]
	v_cndmask_b32_e64 v20, v26, v48, s[6:7]
	v_cndmask_b32_e64 v27, v25, v45, s[6:7]
	v_cndmask_b32_e64 v26, v24, v44, s[6:7]
	v_mov_b32_dpp v46, v34 row_shr:1 row_mask:0xf bank_mask:0xf bound_ctrl:1
	v_mov_b32_dpp v47, v35 row_shr:1 row_mask:0xf bank_mask:0xf bound_ctrl:1
	v_mov_b32_e32 v48, v28
	v_mov_b32_e32 v49, v30
	v_cndmask_b32_e64 v33, v23, v32, s[6:7]
	v_cndmask_b32_e64 v32, v22, v50, s[6:7]
	v_mov_b32_dpp v44, v26 row_shr:1 row_mask:0xf bank_mask:0xf bound_ctrl:1
	v_mov_b32_dpp v45, v27 row_shr:1 row_mask:0xf bank_mask:0xf bound_ctrl:1
	v_pk_mul_f32 v[50:51], v[48:49], v[46:47]
	v_mov_b32_e32 v78, v29
	v_mov_b32_e32 v79, v31
	v_pk_fma_f32 v[50:51], v[78:79], v[44:45], v[50:51]
	v_pk_mul_f32 v[30:31], v[30:31], v[30:31]
	v_pk_mul_f32 v[28:29], v[28:29], v[28:29]
	v_pk_add_f32 v[34:35], v[50:51], v[34:35]
	v_mov_b32_e32 v50, v28
	v_mov_b32_e32 v51, v30
	v_mov_b32_e32 v30, v29
	v_pk_mul_f32 v[46:47], v[78:79], v[46:47]
	v_pk_add_f32 v[28:29], v[50:51], v[30:31] neg_lo:[0,1] neg_hi:[0,1]
	v_pk_add_f32 v[30:31], v[48:49], v[48:49]
	v_pk_fma_f32 v[44:45], v[48:49], v[44:45], v[46:47] neg_lo:[0,0,1] neg_hi:[0,0,1]
	v_pk_mul_f32 v[30:31], v[78:79], v[30:31]
	v_mov_b32_dpp v50, v34 row_shr:2 row_mask:0xf bank_mask:0xf bound_ctrl:1
	v_mov_b32_dpp v51, v35 row_shr:2 row_mask:0xf bank_mask:0xf bound_ctrl:1
	v_pk_add_f32 v[26:27], v[44:45], v[26:27]
	v_pk_mul_f32 v[84:85], v[30:31], v[30:31]
	v_pk_mul_f32 v[46:47], v[30:31], v[50:51]
	v_mov_b32_dpp v44, v26 row_shr:2 row_mask:0xf bank_mask:0xf bound_ctrl:1
	v_mov_b32_dpp v45, v27 row_shr:2 row_mask:0xf bank_mask:0xf bound_ctrl:1
	v_pk_mul_f32 v[82:83], v[28:29], v[50:51]
	v_pk_fma_f32 v[84:85], v[28:29], v[28:29], v[84:85] neg_lo:[0,0,1] neg_hi:[0,0,1]
	v_pk_add_f32 v[86:87], v[28:29], v[28:29]
	v_pk_fma_f32 v[28:29], v[28:29], v[44:45], v[46:47] neg_lo:[0,0,1] neg_hi:[0,0,1]
	v_pk_mul_f32 v[86:87], v[30:31], v[86:87]
	v_pk_add_f32 v[26:27], v[28:29], v[26:27]
	v_pk_fma_f32 v[28:29], v[30:31], v[44:45], v[82:83]
	v_pk_add_f32 v[90:91], v[84:85], v[84:85]
	v_pk_add_f32 v[28:29], v[34:35], v[28:29]
	v_mov_b32_dpp v30, v26 row_shr:4 row_mask:0xf bank_mask:0xf bound_ctrl:1
	v_mov_b32_dpp v31, v27 row_shr:4 row_mask:0xf bank_mask:0xf bound_ctrl:1
	v_mov_b32_dpp v34, v28 row_shr:4 row_mask:0xf bank_mask:0xf bound_ctrl:1
	v_mov_b32_dpp v35, v29 row_shr:4 row_mask:0xf bank_mask:0xf bound_ctrl:1
	v_pk_mul_f32 v[44:45], v[86:87], v[34:35]
	v_pk_mul_f32 v[34:35], v[84:85], v[34:35]
	v_pk_fma_f32 v[44:45], v[84:85], v[30:31], v[44:45] neg_lo:[0,0,1] neg_hi:[0,0,1]
	v_pk_fma_f32 v[30:31], v[86:87], v[30:31], v[34:35]
	v_pk_mul_f32 v[88:89], v[86:87], v[86:87]
	v_pk_add_f32 v[28:29], v[28:29], v[30:31]
	v_pk_mul_f32 v[90:91], v[86:87], v[90:91]
	v_pk_add_f32 v[26:27], v[26:27], v[44:45]
	v_mov_b32_dpp v34, v28 row_shr:8 row_mask:0xf bank_mask:0xf bound_ctrl:1
	v_mov_b32_dpp v35, v29 row_shr:8 row_mask:0xf bank_mask:0xf bound_ctrl:1
	v_pk_fma_f32 v[88:89], v[84:85], v[84:85], v[88:89] neg_lo:[0,0,1] neg_hi:[0,0,1]
	v_mov_b32_dpp v30, v26 row_shr:8 row_mask:0xf bank_mask:0xf bound_ctrl:1
	v_mov_b32_dpp v31, v27 row_shr:8 row_mask:0xf bank_mask:0xf bound_ctrl:1
	v_pk_mul_f32 v[44:45], v[90:91], v[34:35]
	v_mov_b32_dpp v24, v32 row_shr:1 row_mask:0xf bank_mask:0xf bound_ctrl:1
	v_pk_fma_f32 v[44:45], v[88:89], v[30:31], v[44:45] neg_lo:[0,0,1] neg_hi:[0,0,1]
	v_mov_b32_dpp v25, v33 row_shr:1 row_mask:0xf bank_mask:0xf bound_ctrl:1
	v_pk_add_f32 v[46:47], v[26:27], v[44:45]
	v_pk_mul_f32 v[26:27], v[88:89], v[34:35]
	v_mov_b32_dpp v22, v20 row_shr:1 row_mask:0xf bank_mask:0xf bound_ctrl:1
	v_pk_fma_f32 v[26:27], v[90:91], v[30:31], v[26:27]
	v_mov_b32_dpp v23, v21 row_shr:1 row_mask:0xf bank_mask:0xf bound_ctrl:1
	v_pk_add_f32 v[44:45], v[28:29], v[26:27]
	v_mov_b32_e32 v26, v16
	v_mov_b32_e32 v27, v18
	v_pk_mul_f32 v[28:29], v[26:27], v[24:25]
	v_mov_b32_e32 v30, v17
	v_mov_b32_e32 v31, v19
	v_pk_fma_f32 v[28:29], v[30:31], v[22:23], v[28:29]
	v_pk_mul_f32 v[18:19], v[18:19], v[18:19]
	v_pk_mul_f32 v[16:17], v[16:17], v[16:17]
	v_pk_mul_f32 v[24:25], v[30:31], v[24:25]
	v_pk_add_f32 v[28:29], v[28:29], v[32:33]
	v_mov_b32_e32 v32, v16
	v_mov_b32_e32 v33, v18
	v_mov_b32_e32 v18, v17
	v_pk_fma_f32 v[22:23], v[26:27], v[22:23], v[24:25] neg_lo:[0,0,1] neg_hi:[0,0,1]
	v_pk_add_f32 v[16:17], v[32:33], v[18:19] neg_lo:[0,1] neg_hi:[0,1]
	v_pk_add_f32 v[18:19], v[26:27], v[26:27]
	v_mov_b32_dpp v32, v28 row_shr:2 row_mask:0xf bank_mask:0xf bound_ctrl:1
	v_mov_b32_dpp v33, v29 row_shr:2 row_mask:0xf bank_mask:0xf bound_ctrl:1
	v_pk_add_f32 v[20:21], v[22:23], v[20:21]
	v_pk_mul_f32 v[18:19], v[30:31], v[18:19]
	v_pk_mul_f32 v[34:35], v[16:17], v[32:33]
	v_pk_add_f32 v[50:51], v[16:17], v[16:17]
	v_mov_b32_dpp v22, v20 row_shr:2 row_mask:0xf bank_mask:0xf bound_ctrl:1
	v_mov_b32_dpp v23, v21 row_shr:2 row_mask:0xf bank_mask:0xf bound_ctrl:1
	v_pk_mul_f32 v[48:49], v[18:19], v[18:19]
; #define SSM_SCAN_STEP(D, SQ) { _Pragma("unroll") for (int r = 0; r < 4; ++r) { \
;                     const float sr = dppf<DPP_SHR(D)>(Er[r]), si = dppf<DPP_SHR(D)>(Ei[r]); \
;                     Er[r] += mr[r] * sr - mi[r] * si; Ei[r] += mr[r] * si + mi[r] * sr; \
;                     if (SQ) { const float nr = mr[r] * mr[r] - mi[r] * mi[r], ni = 2.f * mr[r] * mi[r]; mr[r] = nr; mi[r] = ni; } } }
; template <bool PASS2>
; __device__ __forceinline__ void ssm_phase(const Params& p, const Frame& F0) {
;     ...
;             for (int i = 0; i < 4; ++i) {
;                 __builtin_amdgcn_sched_barrier(0);
;                 f32x4 Er = (f32x4){0.f, 0.f, 0.f, 0.f}, Ei = Er;
; #pragma unroll
;                 for (int ks = 0; ks < 4; ++ks) { Er = __builtin_amdgcn_mfma_f32_16x16x32_bf16(frag[(i * 4 + ks) * 64], uf[ks], Er, 0, 0, 0);
;                                                  Ei = __builtin_amdgcn_mfma_f32_16x16x32_bf16(frag[((i + 4) * 4 + ks) * 64], uf[ks], Ei, 0, 0, 0); }
;                 const f32x4 ma = m1t[8 * i], mb = m1t[8 * i + 1];
;                 float mr[4] = {ma[0], ma[2], mb[0], mb[2]}, mi[4] = {ma[1], ma[3], mb[1], mb[3]};
;                 float hr[4], hi[4];
; #pragma unroll
;                 for (int r = 0; r < 4; ++r) { hr[r] = dppf<DPP_ROR(1)>(xs[i][r]); hi[r] = dppf<DPP_ROR(1)>(xs[i + 4][r]);
;                     if (j == 0) { Er[r] += mr[r] * hr[r] - mi[r] * hi[r]; Ei[r] += mr[r] * hi[r] + mi[r] * hr[r]; } }
;     ...
;                 SSM_SCAN_STEP(1, 1) SSM_SCAN_STEP(2, 1) SSM_SCAN_STEP(4, 1) SSM_SCAN_STEP(8, 0)
;     ...
;                 xs[i] = Er; xs[i + 4] = Ei;
	v_pk_mul_f32 v[50:51], v[18:19], v[50:51]
	v_pk_mul_f32 v[24:25], v[18:19], v[32:33]
	v_pk_fma_f32 v[18:19], v[18:19], v[22:23], v[34:35]
	v_pk_fma_f32 v[48:49], v[16:17], v[16:17], v[48:49] neg_lo:[0,0,1] neg_hi:[0,0,1]
	v_pk_fma_f32 v[16:17], v[16:17], v[22:23], v[24:25] neg_lo:[0,0,1] neg_hi:[0,0,1]
	v_pk_add_f32 v[18:19], v[28:29], v[18:19]
	v_pk_add_f32 v[16:17], v[20:21], v[16:17]
	v_pk_add_f32 v[82:83], v[48:49], v[48:49]
	v_mov_b32_dpp v22, v18 row_shr:4 row_mask:0xf bank_mask:0xf bound_ctrl:1
	v_mov_b32_dpp v23, v19 row_shr:4 row_mask:0xf bank_mask:0xf bound_ctrl:1
	v_mov_b32_dpp v20, v16 row_shr:4 row_mask:0xf bank_mask:0xf bound_ctrl:1
	v_mov_b32_dpp v21, v17 row_shr:4 row_mask:0xf bank_mask:0xf bound_ctrl:1
	v_pk_mul_f32 v[24:25], v[50:51], v[22:23]
	v_pk_mul_f32 v[22:23], v[48:49], v[22:23]
	v_pk_fma_f32 v[24:25], v[48:49], v[20:21], v[24:25] neg_lo:[0,0,1] neg_hi:[0,0,1]
	v_pk_fma_f32 v[20:21], v[50:51], v[20:21], v[22:23]
	v_pk_mul_f32 v[78:79], v[50:51], v[50:51]
	v_pk_add_f32 v[18:19], v[18:19], v[20:21]
	v_pk_mul_f32 v[82:83], v[50:51], v[82:83]
	v_pk_add_f32 v[16:17], v[16:17], v[24:25]
	v_mov_b32_dpp v22, v18 row_shr:8 row_mask:0xf bank_mask:0xf bound_ctrl:1
	v_mov_b32_dpp v23, v19 row_shr:8 row_mask:0xf bank_mask:0xf bound_ctrl:1
	v_pk_fma_f32 v[78:79], v[48:49], v[48:49], v[78:79] neg_lo:[0,0,1] neg_hi:[0,0,1]
	v_mov_b32_dpp v20, v16 row_shr:8 row_mask:0xf bank_mask:0xf bound_ctrl:1
	v_mov_b32_dpp v21, v17 row_shr:8 row_mask:0xf bank_mask:0xf bound_ctrl:1
	v_pk_mul_f32 v[24:25], v[82:83], v[22:23]
	s_nop 0
	v_pk_fma_f32 v[24:25], v[78:79], v[20:21], v[24:25] neg_lo:[0,0,1] neg_hi:[0,0,1]
	s_nop 0
	v_pk_add_f32 v[50:51], v[16:17], v[24:25]
	v_pk_mul_f32 v[16:17], v[78:79], v[22:23]
	s_nop 0
	v_pk_fma_f32 v[16:17], v[82:83], v[20:21], v[16:17]
	s_nop 0
	v_pk_add_f32 v[48:49], v[18:19], v[16:17]
	s_addk_i32 s0, 0x80
	s_cmpk_eq_i32 s0, 0x180
	s_cbranch_scc0 .LBB0_527
	v_mov_b32_dpp v65, v72 row_ror:1 row_mask:0xf bank_mask:0xf bound_ctrl:1
	v_mov_b32_dpp v64, v70 row_ror:1 row_mask:0xf bank_mask:0xf bound_ctrl:1
	s_waitcnt vmcnt(3)
	v_mfma_f32_16x16x32_bf16 v[16:19], v[130:133], v[12:15], 0
	s_waitcnt vmcnt(2)
	v_mfma_f32_16x16x32_bf16 v[16:19], v[134:137], v[4:7], v[16:19]
	v_mfma_f32_16x16x32_bf16 v[24:27], v[194:197], v[12:15], 0
	v_mfma_f32_16x16x32_bf16 v[24:27], v[198:201], v[4:7], v[24:27]
	s_waitcnt vmcnt(1)
	v_mfma_f32_16x16x32_bf16 v[16:19], v[138:141], v[8:11], v[16:19]
	ds_read_b128 v[20:23], v109
	ds_read_b128 v[82:85], v109 offset:16
	s_waitcnt lgkmcnt(1)
	v_mov_b32_e32 v72, v21
	v_mfma_f32_16x16x32_bf16 v[24:27], v[204:207], v[8:11], v[24:27]
	v_mul_f32_e64 v28, v20, v65
	v_mul_f32_e64 v29, v21, v64
	v_mov_b32_e32 v70, v20
	v_sub_f32_e32 v28, v28, v29
	s_waitcnt vmcnt(0)
	v_mfma_f32_16x16x32_bf16 v[16:19], v[142:145], v[0:3], v[16:19]
	v_mfma_f32_16x16x32_bf16 v[24:27], v[208:211], v[0:3], v[24:27]
	s_nop 6
	v_add_f32_e32 v32, v16, v28
	v_pk_mul_f32 v[28:29], v[20:21], v[64:65]
	v_cndmask_b32_e64 v16, v16, v32, s[6:7]
	v_add_f32_e32 v28, v29, v28
	v_add_f32_e32 v33, v24, v28
	v_mov_b32_dpp v29, v73 row_ror:1 row_mask:0xf bank_mask:0xf bound_ctrl:1
	v_mov_b32_dpp v28, v71 row_ror:1 row_mask:0xf bank_mask:0xf bound_ctrl:1
	v_pk_mul_f32 v[30:31], v[22:23], v[28:29] op_sel:[0,1] op_sel_hi:[1,0]
	v_pk_mul_f32 v[28:29], v[22:23], v[28:29]
	v_sub_f32_e32 v30, v30, v31
	v_add_f32_e32 v28, v29, v28
	v_add_f32_e32 v35, v28, v25
	v_mov_b32_dpp v29, v76 row_ror:1 row_mask:0xf bank_mask:0xf bound_ctrl:1
	v_mov_b32_dpp v28, v74 row_ror:1 row_mask:0xf bank_mask:0xf bound_ctrl:1
	v_add_f32_e32 v34, v30, v17
	s_waitcnt lgkmcnt(0)
	v_pk_mul_f32 v[30:31], v[82:83], v[28:29] op_sel:[0,1] op_sel_hi:[1,0]
	v_pk_mul_f32 v[28:29], v[82:83], v[28:29]
	v_sub_f32_e32 v30, v30, v31
	v_add_f32_e32 v28, v29, v28
	v_add_f32_e32 v65, v28, v26
	v_mov_b32_dpp v29, v77 row_ror:1 row_mask:0xf bank_mask:0xf bound_ctrl:1
	v_mov_b32_dpp v28, v75 row_ror:1 row_mask:0xf bank_mask:0xf bound_ctrl:1
	v_add_f32_e32 v64, v30, v18
	v_pk_mul_f32 v[30:31], v[84:85], v[28:29] op_sel:[0,1] op_sel_hi:[1,0]
	v_pk_mul_f32 v[28:29], v[84:85], v[28:29]
	v_sub_f32_e32 v30, v30, v31
	v_add_f32_e32 v28, v29, v28
	v_cndmask_b32_e64 v25, v25, v35, s[6:7]
	v_cndmask_b32_e64 v24, v24, v33, s[6:7]
	v_add_f32_e32 v30, v30, v19
	v_add_f32_e32 v28, v28, v27
	v_cndmask_b32_e64 v17, v17, v34, s[6:7]
	v_mov_b32_dpp v32, v24 row_shr:1 row_mask:0xf bank_mask:0xf bound_ctrl:1
	v_mov_b32_dpp v33, v25 row_shr:1 row_mask:0xf bank_mask:0xf bound_ctrl:1
	v_mov_b32_e32 v73, v23
	v_cndmask_b32_e64 v29, v27, v28, s[6:7]
	v_cndmask_b32_e64 v28, v26, v65, s[6:7]
	v_cndmask_b32_e64 v27, v19, v30, s[6:7]
	v_cndmask_b32_e64 v26, v18, v64, s[6:7]
	v_mov_b32_dpp v30, v16 row_shr:1 row_mask:0xf bank_mask:0xf bound_ctrl:1
	v_mov_b32_dpp v31, v17 row_shr:1 row_mask:0xf bank_mask:0xf bound_ctrl:1
	v_mov_b32_e32 v71, v22
	v_pk_mul_f32 v[18:19], v[72:73], v[32:33]
	v_pk_mul_f32 v[32:33], v[70:71], v[32:33]
	v_pk_fma_f32 v[18:19], v[70:71], v[30:31], v[18:19] neg_lo:[0,0,1] neg_hi:[0,0,1]
	v_pk_fma_f32 v[30:31], v[72:73], v[30:31], v[32:33]
	v_pk_add_f32 v[74:75], v[18:19], v[16:17]
	v_pk_mul_f32 v[16:17], v[22:23], v[22:23]
	v_pk_mul_f32 v[18:19], v[20:21], v[20:21]
	v_mov_b32_e32 v21, v16
	v_mov_b32_e32 v20, v18
	v_mov_b32_e32 v16, v19
	v_pk_add_f32 v[20:21], v[20:21], v[16:17] neg_lo:[0,1] neg_hi:[0,1]
	v_pk_add_f32 v[16:17], v[70:71], v[70:71]
	v_pk_add_f32 v[24:25], v[30:31], v[24:25]
	v_pk_mul_f32 v[22:23], v[72:73], v[16:17]
	v_mov_b32_dpp v76, v74 row_shr:2 row_mask:0xf bank_mask:0xf bound_ctrl:1
	v_mov_b32_dpp v30, v24 row_shr:2 row_mask:0xf bank_mask:0xf bound_ctrl:1
; #define SSM_SCAN_STEP(D, SQ) { _Pragma("unroll") for (int r = 0; r < 4; ++r) { \
;                     const float sr = dppf<DPP_SHR(D)>(Er[r]), si = dppf<DPP_SHR(D)>(Ei[r]); \
;                     Er[r] += mr[r] * sr - mi[r] * si; Ei[r] += mr[r] * si + mi[r] * sr; \
;                     if (SQ) { const float nr = mr[r] * mr[r] - mi[r] * mi[r], ni = 2.f * mr[r] * mi[r]; mr[r] = nr; mi[r] = ni; } } }
; template <bool PASS2>
; __device__ __forceinline__ void ssm_phase(const Params& p, const Frame& F0) {
;     ...
;             for (int i = 0; i < 4; ++i) {
;                 __builtin_amdgcn_sched_barrier(0);
;                 f32x4 Er = (f32x4){0.f, 0.f, 0.f, 0.f}, Ei = Er;
; #pragma unroll
;                 for (int ks = 0; ks < 4; ++ks) { Er = __builtin_amdgcn_mfma_f32_16x16x32_bf16(frag[(i * 4 + ks) * 64], uf[ks], Er, 0, 0, 0);
;                                                  Ei = __builtin_amdgcn_mfma_f32_16x16x32_bf16(frag[((i + 4) * 4 + ks) * 64], uf[ks], Ei, 0, 0, 0); }
;                 const f32x4 ma = m1t[8 * i], mb = m1t[8 * i + 1];
;                 float mr[4] = {ma[0], ma[2], mb[0], mb[2]}, mi[4] = {ma[1], ma[3], mb[1], mb[3]};
;                 float hr[4], hi[4];
; #pragma unroll
;                 for (int r = 0; r < 4; ++r) { hr[r] = dppf<DPP_ROR(1)>(xs[i][r]); hi[r] = dppf<DPP_ROR(1)>(xs[i + 4][r]);
;                     if (j == 0) { Er[r] += mr[r] * hr[r] - mi[r] * hi[r]; Ei[r] += mr[r] * hi[r] + mi[r] * hr[r]; } }
;     ...
;                 SSM_SCAN_STEP(1, 1) SSM_SCAN_STEP(2, 1) SSM_SCAN_STEP(4, 1) SSM_SCAN_STEP(8, 0)
	v_mov_b32_dpp v31, v25 row_shr:2 row_mask:0xf bank_mask:0xf bound_ctrl:1
	v_mov_b32_dpp v77, v75 row_shr:2 row_mask:0xf bank_mask:0xf bound_ctrl:1
	v_pk_mul_f32 v[16:17], v[22:23], v[22:23]
	v_pk_mul_f32 v[32:33], v[22:23], v[30:31]
	v_pk_fma_f32 v[16:17], v[20:21], v[20:21], v[16:17] neg_lo:[0,0,1] neg_hi:[0,0,1]
	v_pk_add_f32 v[18:19], v[20:21], v[20:21]
	v_pk_fma_f32 v[32:33], v[20:21], v[76:77], v[32:33] neg_lo:[0,0,1] neg_hi:[0,0,1]
	v_pk_mul_f32 v[20:21], v[20:21], v[30:31]
	v_pk_mul_f32 v[18:19], v[22:23], v[18:19]
	v_pk_fma_f32 v[20:21], v[22:23], v[76:77], v[20:21]
	v_pk_add_f32 v[32:33], v[32:33], v[74:75]
	v_pk_add_f32 v[22:23], v[24:25], v[20:21]
	v_mov_b32_dpp v64, v28 row_shr:1 row_mask:0xf bank_mask:0xf bound_ctrl:1
	v_mov_b32_dpp v24, v32 row_shr:4 row_mask:0xf bank_mask:0xf bound_ctrl:1
	v_mov_b32_dpp v30, v22 row_shr:4 row_mask:0xf bank_mask:0xf bound_ctrl:1
	v_mov_b32_dpp v31, v23 row_shr:4 row_mask:0xf bank_mask:0xf bound_ctrl:1
	v_mov_b32_dpp v25, v33 row_shr:4 row_mask:0xf bank_mask:0xf bound_ctrl:1
	v_pk_mul_f32 v[20:21], v[18:19], v[30:31]
	v_pk_mul_f32 v[30:31], v[16:17], v[30:31]
	v_pk_fma_f32 v[20:21], v[16:17], v[24:25], v[20:21] neg_lo:[0,0,1] neg_hi:[0,0,1]
	v_mov_b32_dpp v65, v29 row_shr:1 row_mask:0xf bank_mask:0xf bound_ctrl:1
	v_pk_add_f32 v[20:21], v[32:33], v[20:21]
	v_pk_fma_f32 v[24:25], v[18:19], v[24:25], v[30:31]
	v_mov_b32_e32 v32, v83
	v_mov_b32_e32 v33, v85
	v_mov_b32_dpp v34, v26 row_shr:1 row_mask:0xf bank_mask:0xf bound_ctrl:1
	v_mov_b32_dpp v35, v27 row_shr:1 row_mask:0xf bank_mask:0xf bound_ctrl:1
	v_pk_add_f32 v[22:23], v[22:23], v[24:25]
	v_mov_b32_e32 v30, v82
	v_mov_b32_e32 v31, v84
	v_pk_mul_f32 v[24:25], v[32:33], v[64:65]
	s_nop 0
	v_pk_fma_f32 v[24:25], v[30:31], v[34:35], v[24:25] neg_lo:[0,0,1] neg_hi:[0,0,1]
	s_nop 0
	v_pk_add_f32 v[70:71], v[24:25], v[26:27]
	v_pk_mul_f32 v[24:25], v[84:85], v[84:85]
	v_pk_mul_f32 v[26:27], v[82:83], v[82:83]
	v_mov_b32_e32 v73, v24
	v_mov_b32_e32 v72, v26
	v_mov_b32_e32 v24, v27
	v_pk_add_f32 v[72:73], v[72:73], v[24:25] neg_lo:[0,1] neg_hi:[0,1]
	v_pk_add_f32 v[24:25], v[30:31], v[30:31]
	v_pk_mul_f32 v[30:31], v[30:31], v[64:65]
	v_pk_mul_f32 v[74:75], v[32:33], v[24:25]
	v_pk_fma_f32 v[30:31], v[32:33], v[34:35], v[30:31]
	v_mov_b32_dpp v76, v70 row_shr:2 row_mask:0xf bank_mask:0xf bound_ctrl:1
	v_pk_add_f32 v[28:29], v[30:31], v[28:29]
	v_mov_b32_dpp v77, v71 row_shr:2 row_mask:0xf bank_mask:0xf bound_ctrl:1
	v_pk_add_f32 v[26:27], v[72:73], v[72:73]
	v_mov_b32_dpp v30, v28 row_shr:2 row_mask:0xf bank_mask:0xf bound_ctrl:1
	v_mov_b32_dpp v31, v29 row_shr:2 row_mask:0xf bank_mask:0xf bound_ctrl:1
	v_pk_mul_f32 v[32:33], v[74:75], v[30:31]
	v_pk_mul_f32 v[30:31], v[72:73], v[30:31]
	v_pk_fma_f32 v[32:33], v[72:73], v[76:77], v[32:33] neg_lo:[0,0,1] neg_hi:[0,0,1]
	v_pk_fma_f32 v[30:31], v[74:75], v[76:77], v[30:31]
	v_pk_mul_f32 v[24:25], v[74:75], v[74:75]
	v_pk_add_f32 v[30:31], v[28:29], v[30:31]
	v_pk_mul_f32 v[26:27], v[74:75], v[26:27]
	v_pk_add_f32 v[32:33], v[70:71], v[32:33]
	v_mov_b32_dpp v64, v30 row_shr:4 row_mask:0xf bank_mask:0xf bound_ctrl:1
	v_mov_b32_dpp v65, v31 row_shr:4 row_mask:0xf bank_mask:0xf bound_ctrl:1
	v_pk_fma_f32 v[24:25], v[72:73], v[72:73], v[24:25] neg_lo:[0,0,1] neg_hi:[0,0,1]
	v_mov_b32_dpp v34, v32 row_shr:4 row_mask:0xf bank_mask:0xf bound_ctrl:1
	v_mov_b32_dpp v35, v33 row_shr:4 row_mask:0xf bank_mask:0xf bound_ctrl:1
	v_pk_mul_f32 v[28:29], v[26:27], v[64:65]
	s_nop 0
	v_pk_fma_f32 v[28:29], v[24:25], v[34:35], v[28:29] neg_lo:[0,0,1] neg_hi:[0,0,1]
	s_nop 0
	v_pk_add_f32 v[28:29], v[32:33], v[28:29]
	v_pk_mul_f32 v[32:33], v[24:25], v[64:65]
	v_mov_b32_dpp v64, v22 row_shr:8 row_mask:0xf bank_mask:0xf bound_ctrl:1
	v_pk_fma_f32 v[32:33], v[26:27], v[34:35], v[32:33]
	v_mov_b32_dpp v65, v23 row_shr:8 row_mask:0xf bank_mask:0xf bound_ctrl:1
	v_pk_add_f32 v[32:33], v[30:31], v[32:33]
	v_mov_b32_dpp v30, v20 row_shr:8 row_mask:0xf bank_mask:0xf bound_ctrl:1
	v_mov_b32_dpp v31, v21 row_shr:8 row_mask:0xf bank_mask:0xf bound_ctrl:1
	v_mov_b32_dpp v34, v28 row_shr:8 row_mask:0xf bank_mask:0xf bound_ctrl:1
	v_mov_b32_dpp v70, v32 row_shr:8 row_mask:0xf bank_mask:0xf bound_ctrl:1
	v_mov_b32_dpp v35, v29 row_shr:8 row_mask:0xf bank_mask:0xf bound_ctrl:1
	v_mov_b32_dpp v71, v33 row_shr:8 row_mask:0xf bank_mask:0xf bound_ctrl:1
	v_mov_b32_dpp v101, v62 row_ror:1 row_mask:0xf bank_mask:0xf bound_ctrl:1
	v_mov_b32_dpp v100, v60 row_ror:1 row_mask:0xf bank_mask:0xf bound_ctrl:1
	v_mfma_f32_16x16x32_bf16 v[72:75], v[146:149], v[12:15], 0
	v_mov_b32_dpp v63, v63 row_ror:1 row_mask:0xf bank_mask:0xf bound_ctrl:1
	v_mov_b32_dpp v62, v61 row_ror:1 row_mask:0xf bank_mask:0xf bound_ctrl:1
	v_mfma_f32_16x16x32_bf16 v[72:75], v[150:153], v[4:7], v[72:75]
	v_mfma_f32_16x16x32_bf16 v[80:83], v[212:215], v[12:15], 0
	v_mfma_f32_16x16x32_bf16 v[80:83], v[216:219], v[4:7], v[80:83]
	v_mfma_f32_16x16x32_bf16 v[72:75], v[154:157], v[8:11], v[72:75]
	ds_read_b128 v[76:79], v109 offset:128
	ds_read_b128 v[96:99], v109 offset:144
	v_mfma_f32_16x16x32_bf16 v[80:83], v[220:223], v[8:11], v[80:83]
	s_waitcnt lgkmcnt(1)
	v_pk_mul_f32 v[84:85], v[76:77], v[100:101] op_sel:[0,1] op_sel_hi:[1,0]
	s_nop 0
	v_sub_f32_e32 v60, v84, v85
	v_mfma_f32_16x16x32_bf16 v[72:75], v[158:161], v[0:3], v[72:75]
	v_mul_f32_e64 v84, v76, v100
	v_mul_f32_e64 v85, v77, v101
	v_mov_b32_e32 v88, v77
	v_mov_b32_e32 v89, v79
	v_mfma_f32_16x16x32_bf16 v[80:83], v[224:227], v[0:3], v[80:83]
	s_nop 2
	v_add_f32_e32 v86, v72, v60
	v_add_f32_e32 v60, v85, v84
	s_nop 2
	v_add_f32_e32 v84, v80, v60
	v_pk_mul_f32 v[60:61], v[78:79], v[62:63] op_sel:[0,1] op_sel_hi:[1,0]
	s_nop 0
	v_sub_f32_e32 v60, v60, v61
	v_add_f32_e32 v85, v60, v73
	v_pk_mul_f32 v[60:61], v[78:79], v[62:63]
	s_nop 0
	v_add_f32_e32 v60, v61, v60
	v_add_f32_e32 v87, v60, v81
	v_mov_b32_dpp v61, v68 row_ror:1 row_mask:0xf bank_mask:0xf bound_ctrl:1
	v_mov_b32_dpp v60, v66 row_ror:1 row_mask:0xf bank_mask:0xf bound_ctrl:1
	s_waitcnt lgkmcnt(0)
; #define SSM_SCAN_STEP(D, SQ) { _Pragma("unroll") for (int r = 0; r < 4; ++r) { \
;                     const float sr = dppf<DPP_SHR(D)>(Er[r]), si = dppf<DPP_SHR(D)>(Ei[r]); \
;                     Er[r] += mr[r] * sr - mi[r] * si; Ei[r] += mr[r] * si + mi[r] * sr; \
;                     if (SQ) { const float nr = mr[r] * mr[r] - mi[r] * mi[r], ni = 2.f * mr[r] * mi[r]; mr[r] = nr; mi[r] = ni; } } }
; template <bool PASS2>
; __device__ __forceinline__ void ssm_phase(const Params& p, const Frame& F0) {
;     ...
;                 const f32x4 ma = m1t[8 * i], mb = m1t[8 * i + 1];
;                 float mr[4] = {ma[0], ma[2], mb[0], mb[2]}, mi[4] = {ma[1], ma[3], mb[1], mb[3]};
;                 float hr[4], hi[4];
; #pragma unroll
;                 for (int r = 0; r < 4; ++r) { hr[r] = dppf<DPP_ROR(1)>(xs[i][r]); hi[r] = dppf<DPP_ROR(1)>(xs[i + 4][r]);
;                     if (j == 0) { Er[r] += mr[r] * hr[r] - mi[r] * hi[r]; Ei[r] += mr[r] * hi[r] + mi[r] * hr[r]; } }
;     ...
;                 SSM_SCAN_STEP(1, 1) SSM_SCAN_STEP(2, 1) SSM_SCAN_STEP(4, 1) SSM_SCAN_STEP(8, 0)
	v_pk_mul_f32 v[62:63], v[96:97], v[60:61] op_sel:[0,1] op_sel_hi:[1,0]
	v_pk_mul_f32 v[60:61], v[96:97], v[60:61]
	v_sub_f32_e32 v62, v62, v63
	v_add_f32_e32 v60, v61, v60
	v_add_f32_e32 v66, v60, v82
	v_mov_b32_dpp v61, v69 row_ror:1 row_mask:0xf bank_mask:0xf bound_ctrl:1
	v_mov_b32_dpp v60, v67 row_ror:1 row_mask:0xf bank_mask:0xf bound_ctrl:1
	v_add_f32_e32 v68, v62, v74
	v_pk_mul_f32 v[62:63], v[98:99], v[60:61] op_sel:[0,1] op_sel_hi:[1,0]
	v_pk_mul_f32 v[60:61], v[98:99], v[60:61]
	v_sub_f32_e32 v62, v62, v63
	v_add_f32_e32 v60, v61, v60
	v_add_f32_e32 v60, v60, v83
	v_cndmask_b32_e64 v82, v82, v66, s[6:7]
	v_cndmask_b32_e64 v67, v81, v87, s[6:7]
	v_cndmask_b32_e64 v66, v80, v84, s[6:7]
	v_add_f32_e32 v62, v62, v75
	v_cndmask_b32_e64 v83, v83, v60, s[6:7]
	v_cndmask_b32_e64 v61, v73, v85, s[6:7]
	v_cndmask_b32_e64 v60, v72, v86, s[6:7]
	v_mov_b32_dpp v72, v66 row_shr:1 row_mask:0xf bank_mask:0xf bound_ctrl:1
	v_mov_b32_dpp v73, v67 row_shr:1 row_mask:0xf bank_mask:0xf bound_ctrl:1
	v_cndmask_b32_e64 v75, v75, v62, s[6:7]
	v_cndmask_b32_e64 v74, v74, v68, s[6:7]
	v_mov_b32_dpp v68, v60 row_shr:1 row_mask:0xf bank_mask:0xf bound_ctrl:1
	v_mov_b32_dpp v69, v61 row_shr:1 row_mask:0xf bank_mask:0xf bound_ctrl:1
	v_mov_b32_e32 v86, v76
	v_mov_b32_e32 v87, v78
	v_pk_mul_f32 v[62:63], v[88:89], v[72:73]
	v_pk_mul_f32 v[72:73], v[86:87], v[72:73]
	v_pk_fma_f32 v[62:63], v[86:87], v[68:69], v[62:63] neg_lo:[0,0,1] neg_hi:[0,0,1]
	v_pk_fma_f32 v[68:69], v[88:89], v[68:69], v[72:73]
	v_pk_add_f32 v[90:91], v[62:63], v[60:61]
	v_pk_mul_f32 v[60:61], v[78:79], v[78:79]
	v_pk_mul_f32 v[62:63], v[76:77], v[76:77]
	v_mov_b32_e32 v77, v60
	v_mov_b32_e32 v76, v62
	v_mov_b32_e32 v60, v63
	v_pk_add_f32 v[76:77], v[76:77], v[60:61] neg_lo:[0,1] neg_hi:[0,1]
	v_pk_add_f32 v[60:61], v[86:87], v[86:87]
	v_pk_add_f32 v[66:67], v[68:69], v[66:67]
	v_pk_mul_f32 v[78:79], v[88:89], v[60:61]
	v_mov_b32_dpp v92, v90 row_shr:2 row_mask:0xf bank_mask:0xf bound_ctrl:1
	v_mov_b32_dpp v68, v66 row_shr:2 row_mask:0xf bank_mask:0xf bound_ctrl:1
	v_mov_b32_dpp v69, v67 row_shr:2 row_mask:0xf bank_mask:0xf bound_ctrl:1
	v_mov_b32_dpp v93, v91 row_shr:2 row_mask:0xf bank_mask:0xf bound_ctrl:1
	v_pk_mul_f32 v[72:73], v[78:79], v[68:69]
	v_pk_mul_f32 v[68:69], v[76:77], v[68:69]
	v_pk_add_f32 v[62:63], v[76:77], v[76:77]
	v_pk_fma_f32 v[68:69], v[78:79], v[92:93], v[68:69]
	v_pk_fma_f32 v[72:73], v[76:77], v[92:93], v[72:73] neg_lo:[0,0,1] neg_hi:[0,0,1]
	v_pk_add_f32 v[68:69], v[66:67], v[68:69]
	v_pk_mul_f32 v[60:61], v[78:79], v[78:79]
	v_pk_mul_f32 v[62:63], v[78:79], v[62:63]
	v_pk_add_f32 v[72:73], v[72:73], v[90:91]
	v_mov_b32_dpp v78, v68 row_shr:4 row_mask:0xf bank_mask:0xf bound_ctrl:1
	v_mov_b32_dpp v79, v69 row_shr:4 row_mask:0xf bank_mask:0xf bound_ctrl:1
	v_pk_fma_f32 v[60:61], v[76:77], v[76:77], v[60:61] neg_lo:[0,0,1] neg_hi:[0,0,1]
	v_mov_b32_dpp v76, v72 row_shr:4 row_mask:0xf bank_mask:0xf bound_ctrl:1
	v_mov_b32_dpp v77, v73 row_shr:4 row_mask:0xf bank_mask:0xf bound_ctrl:1
	v_pk_mul_f32 v[66:67], v[62:63], v[78:79]
	v_mov_b32_dpp v84, v82 row_shr:1 row_mask:0xf bank_mask:0xf bound_ctrl:1
	v_pk_fma_f32 v[66:67], v[60:61], v[76:77], v[66:67] neg_lo:[0,0,1] neg_hi:[0,0,1]
	v_mov_b32_dpp v85, v83 row_shr:1 row_mask:0xf bank_mask:0xf bound_ctrl:1
	v_pk_add_f32 v[66:67], v[72:73], v[66:67]
	v_pk_mul_f32 v[72:73], v[60:61], v[78:79]
	v_mov_b32_e32 v78, v97
	v_pk_fma_f32 v[72:73], v[62:63], v[76:77], v[72:73]
	v_mov_b32_e32 v79, v99
	v_mov_b32_dpp v80, v74 row_shr:1 row_mask:0xf bank_mask:0xf bound_ctrl:1
	v_mov_b32_dpp v81, v75 row_shr:1 row_mask:0xf bank_mask:0xf bound_ctrl:1
	v_pk_add_f32 v[68:69], v[68:69], v[72:73]
	v_mov_b32_e32 v76, v96
	v_mov_b32_e32 v77, v98
	v_pk_mul_f32 v[72:73], v[78:79], v[84:85]
	s_nop 0
	v_pk_fma_f32 v[72:73], v[76:77], v[80:81], v[72:73] neg_lo:[0,0,1] neg_hi:[0,0,1]
	s_nop 0
	v_pk_add_f32 v[86:87], v[72:73], v[74:75]
	v_pk_mul_f32 v[72:73], v[98:99], v[98:99]
	v_pk_mul_f32 v[74:75], v[96:97], v[96:97]
	v_mov_b32_e32 v89, v72
	v_mov_b32_e32 v88, v74
	v_mov_b32_e32 v72, v75
	v_pk_add_f32 v[88:89], v[88:89], v[72:73] neg_lo:[0,1] neg_hi:[0,1]
	v_pk_add_f32 v[72:73], v[76:77], v[76:77]
	v_pk_mul_f32 v[76:77], v[76:77], v[84:85]
	v_pk_mul_f32 v[90:91], v[78:79], v[72:73]
	v_pk_fma_f32 v[76:77], v[78:79], v[80:81], v[76:77]
	v_mov_b32_dpp v92, v86 row_shr:2 row_mask:0xf bank_mask:0xf bound_ctrl:1
	v_pk_add_f32 v[76:77], v[76:77], v[82:83]
	v_mov_b32_dpp v93, v87 row_shr:2 row_mask:0xf bank_mask:0xf bound_ctrl:1
	v_pk_add_f32 v[74:75], v[88:89], v[88:89]
	v_mov_b32_dpp v78, v76 row_shr:2 row_mask:0xf bank_mask:0xf bound_ctrl:1
	v_mov_b32_dpp v79, v77 row_shr:2 row_mask:0xf bank_mask:0xf bound_ctrl:1
	v_pk_mul_f32 v[80:81], v[90:91], v[78:79]
	v_pk_mul_f32 v[78:79], v[88:89], v[78:79]
	v_pk_fma_f32 v[80:81], v[88:89], v[92:93], v[80:81] neg_lo:[0,0,1] neg_hi:[0,0,1]
	v_pk_fma_f32 v[78:79], v[90:91], v[92:93], v[78:79]
	v_pk_mul_f32 v[72:73], v[90:91], v[90:91]
	v_pk_add_f32 v[78:79], v[76:77], v[78:79]
	v_pk_mul_f32 v[74:75], v[90:91], v[74:75]
	v_pk_add_f32 v[80:81], v[86:87], v[80:81]
	v_mov_b32_dpp v84, v78 row_shr:4 row_mask:0xf bank_mask:0xf bound_ctrl:1
	v_mov_b32_dpp v85, v79 row_shr:4 row_mask:0xf bank_mask:0xf bound_ctrl:1
	v_pk_fma_f32 v[72:73], v[88:89], v[88:89], v[72:73] neg_lo:[0,0,1] neg_hi:[0,0,1]
	v_mov_b32_dpp v82, v80 row_shr:4 row_mask:0xf bank_mask:0xf bound_ctrl:1
	v_mov_b32_dpp v83, v81 row_shr:4 row_mask:0xf bank_mask:0xf bound_ctrl:1
	v_pk_mul_f32 v[76:77], v[74:75], v[84:85]
	s_nop 0
	v_pk_fma_f32 v[76:77], v[72:73], v[82:83], v[76:77] neg_lo:[0,0,1] neg_hi:[0,0,1]
	s_nop 0
	v_pk_add_f32 v[76:77], v[80:81], v[76:77]
; #define SSM_SCAN_STEP(D, SQ) { _Pragma("unroll") for (int r = 0; r < 4; ++r) { \
;                     const float sr = dppf<DPP_SHR(D)>(Er[r]), si = dppf<DPP_SHR(D)>(Ei[r]); \
;                     Er[r] += mr[r] * sr - mi[r] * si; Ei[r] += mr[r] * si + mi[r] * sr; \
;                     if (SQ) { const float nr = mr[r] * mr[r] - mi[r] * mi[r], ni = 2.f * mr[r] * mi[r]; mr[r] = nr; mi[r] = ni; } } }
; template <bool PASS2>
; __device__ __forceinline__ void ssm_phase(const Params& p, const Frame& F0) {
;     ...
;             for (int i = 0; i < 4; ++i) {
;                 __builtin_amdgcn_sched_barrier(0);
;                 f32x4 Er = (f32x4){0.f, 0.f, 0.f, 0.f}, Ei = Er;
; #pragma unroll
;                 for (int ks = 0; ks < 4; ++ks) { Er = __builtin_amdgcn_mfma_f32_16x16x32_bf16(frag[(i * 4 + ks) * 64], uf[ks], Er, 0, 0, 0);
;                                                  Ei = __builtin_amdgcn_mfma_f32_16x16x32_bf16(frag[((i + 4) * 4 + ks) * 64], uf[ks], Ei, 0, 0, 0); }
;                 const f32x4 ma = m1t[8 * i], mb = m1t[8 * i + 1];
;                 float mr[4] = {ma[0], ma[2], mb[0], mb[2]}, mi[4] = {ma[1], ma[3], mb[1], mb[3]};
;                 float hr[4], hi[4];
; #pragma unroll
;                 for (int r = 0; r < 4; ++r) { hr[r] = dppf<DPP_ROR(1)>(xs[i][r]); hi[r] = dppf<DPP_ROR(1)>(xs[i + 4][r]);
;                     if (j == 0) { Er[r] += mr[r] * hr[r] - mi[r] * hi[r]; Ei[r] += mr[r] * hi[r] + mi[r] * hr[r]; } }
;     ...
;                 SSM_SCAN_STEP(1, 1) SSM_SCAN_STEP(2, 1) SSM_SCAN_STEP(4, 1) SSM_SCAN_STEP(8, 0)
	v_pk_mul_f32 v[80:81], v[72:73], v[84:85]
	v_mov_b32_dpp v84, v68 row_shr:8 row_mask:0xf bank_mask:0xf bound_ctrl:1
	v_pk_fma_f32 v[80:81], v[74:75], v[82:83], v[80:81]
	v_mov_b32_dpp v85, v69 row_shr:8 row_mask:0xf bank_mask:0xf bound_ctrl:1
	v_pk_add_f32 v[80:81], v[78:79], v[80:81]
	v_mov_b32_dpp v78, v66 row_shr:8 row_mask:0xf bank_mask:0xf bound_ctrl:1
	v_mov_b32_dpp v79, v67 row_shr:8 row_mask:0xf bank_mask:0xf bound_ctrl:1
	v_mov_b32_dpp v82, v76 row_shr:8 row_mask:0xf bank_mask:0xf bound_ctrl:1
	v_mov_b32_dpp v86, v80 row_shr:8 row_mask:0xf bank_mask:0xf bound_ctrl:1
	v_mov_b32_dpp v83, v77 row_shr:8 row_mask:0xf bank_mask:0xf bound_ctrl:1
	v_mov_b32_dpp v87, v81 row_shr:8 row_mask:0xf bank_mask:0xf bound_ctrl:1
	v_mov_b32_dpp v123, v54 row_ror:1 row_mask:0xf bank_mask:0xf bound_ctrl:1
	v_mov_b32_dpp v122, v52 row_ror:1 row_mask:0xf bank_mask:0xf bound_ctrl:1
	v_mfma_f32_16x16x32_bf16 v[88:91], v[162:165], v[12:15], 0
	v_mov_b32_dpp v55, v55 row_ror:1 row_mask:0xf bank_mask:0xf bound_ctrl:1
	v_mov_b32_dpp v54, v53 row_ror:1 row_mask:0xf bank_mask:0xf bound_ctrl:1
	v_mfma_f32_16x16x32_bf16 v[88:91], v[166:169], v[4:7], v[88:91]
	v_mfma_f32_16x16x32_bf16 v[96:99], v[228:231], v[12:15], 0
	v_mfma_f32_16x16x32_bf16 v[96:99], v[232:235], v[4:7], v[96:99]
	v_mfma_f32_16x16x32_bf16 v[88:91], v[170:173], v[8:11], v[88:91]
	ds_read_b128 v[92:95], v109 offset:256
	ds_read_b128 v[118:121], v109 offset:272
	v_mfma_f32_16x16x32_bf16 v[96:99], v[236:239], v[8:11], v[96:99]
	s_waitcnt lgkmcnt(1)
	v_pk_mul_f32 v[100:101], v[92:93], v[122:123] op_sel:[0,1] op_sel_hi:[1,0]
	s_nop 0
	v_sub_f32_e32 v52, v100, v101
	v_mfma_f32_16x16x32_bf16 v[88:91], v[174:177], v[0:3], v[88:91]
	v_mul_f32_e64 v100, v92, v122
	v_mul_f32_e64 v101, v93, v123
	v_mov_b32_e32 v110, v93
	v_mov_b32_e32 v111, v95
	v_mfma_f32_16x16x32_bf16 v[96:99], v[240:243], v[0:3], v[96:99]
	s_nop 2
	v_add_f32_e32 v102, v88, v52
	v_add_f32_e32 v52, v101, v100
	s_nop 2
	v_add_f32_e32 v100, v96, v52
	v_pk_mul_f32 v[52:53], v[94:95], v[54:55] op_sel:[0,1] op_sel_hi:[1,0]
	s_nop 0
	v_sub_f32_e32 v52, v52, v53
	v_add_f32_e32 v101, v52, v89
	v_pk_mul_f32 v[52:53], v[94:95], v[54:55]
	s_nop 0
	v_add_f32_e32 v52, v53, v52
	v_add_f32_e32 v103, v52, v97
	v_mov_b32_dpp v53, v58 row_ror:1 row_mask:0xf bank_mask:0xf bound_ctrl:1
	v_mov_b32_dpp v52, v56 row_ror:1 row_mask:0xf bank_mask:0xf bound_ctrl:1
	s_waitcnt lgkmcnt(0)
	v_pk_mul_f32 v[54:55], v[118:119], v[52:53] op_sel:[0,1] op_sel_hi:[1,0]
	v_pk_mul_f32 v[52:53], v[118:119], v[52:53]
	v_sub_f32_e32 v54, v54, v55
	v_add_f32_e32 v52, v53, v52
	v_add_f32_e32 v56, v52, v98
	v_mov_b32_dpp v53, v59 row_ror:1 row_mask:0xf bank_mask:0xf bound_ctrl:1
	v_mov_b32_dpp v52, v57 row_ror:1 row_mask:0xf bank_mask:0xf bound_ctrl:1
	v_add_f32_e32 v58, v54, v90
	v_pk_mul_f32 v[54:55], v[120:121], v[52:53] op_sel:[0,1] op_sel_hi:[1,0]
	v_pk_mul_f32 v[52:53], v[120:121], v[52:53]
	v_sub_f32_e32 v54, v54, v55
	v_add_f32_e32 v52, v53, v52
	v_add_f32_e32 v52, v52, v99
	v_cndmask_b32_e64 v98, v98, v56, s[6:7]
	v_cndmask_b32_e64 v57, v97, v103, s[6:7]
	v_cndmask_b32_e64 v56, v96, v100, s[6:7]
	v_add_f32_e32 v54, v54, v91
	v_cndmask_b32_e64 v99, v99, v52, s[6:7]
	v_cndmask_b32_e64 v53, v89, v101, s[6:7]
	v_cndmask_b32_e64 v52, v88, v102, s[6:7]
	v_mov_b32_dpp v88, v56 row_shr:1 row_mask:0xf bank_mask:0xf bound_ctrl:1
	v_mov_b32_dpp v89, v57 row_shr:1 row_mask:0xf bank_mask:0xf bound_ctrl:1
	v_cndmask_b32_e64 v91, v91, v54, s[6:7]
	v_cndmask_b32_e64 v90, v90, v58, s[6:7]
	v_mov_b32_dpp v58, v52 row_shr:1 row_mask:0xf bank_mask:0xf bound_ctrl:1
	v_mov_b32_dpp v59, v53 row_shr:1 row_mask:0xf bank_mask:0xf bound_ctrl:1
	v_mov_b32_e32 v102, v92
	v_mov_b32_e32 v103, v94
	v_pk_mul_f32 v[54:55], v[110:111], v[88:89]
	v_pk_mul_f32 v[88:89], v[102:103], v[88:89]
	v_pk_fma_f32 v[54:55], v[102:103], v[58:59], v[54:55] neg_lo:[0,0,1] neg_hi:[0,0,1]
	v_pk_fma_f32 v[58:59], v[110:111], v[58:59], v[88:89]
	v_pk_add_f32 v[112:113], v[54:55], v[52:53]
	v_pk_mul_f32 v[52:53], v[94:95], v[94:95]
	v_pk_mul_f32 v[54:55], v[92:93], v[92:93]
	v_mov_b32_e32 v93, v52
	v_mov_b32_e32 v92, v54
	v_mov_b32_e32 v52, v55
	v_pk_add_f32 v[92:93], v[92:93], v[52:53] neg_lo:[0,1] neg_hi:[0,1]
	v_pk_add_f32 v[52:53], v[102:103], v[102:103]
	v_pk_add_f32 v[56:57], v[58:59], v[56:57]
	v_pk_mul_f32 v[94:95], v[110:111], v[52:53]
	v_mov_b32_dpp v114, v112 row_shr:2 row_mask:0xf bank_mask:0xf bound_ctrl:1
	v_mov_b32_dpp v58, v56 row_shr:2 row_mask:0xf bank_mask:0xf bound_ctrl:1
	v_mov_b32_dpp v59, v57 row_shr:2 row_mask:0xf bank_mask:0xf bound_ctrl:1
	v_mov_b32_dpp v115, v113 row_shr:2 row_mask:0xf bank_mask:0xf bound_ctrl:1
	v_pk_mul_f32 v[88:89], v[94:95], v[58:59]
	v_pk_mul_f32 v[58:59], v[92:93], v[58:59]
	v_pk_add_f32 v[54:55], v[92:93], v[92:93]
	v_pk_fma_f32 v[58:59], v[94:95], v[114:115], v[58:59]
	v_pk_fma_f32 v[88:89], v[92:93], v[114:115], v[88:89] neg_lo:[0,0,1] neg_hi:[0,0,1]
	v_pk_add_f32 v[58:59], v[56:57], v[58:59]
	v_pk_mul_f32 v[52:53], v[94:95], v[94:95]
	v_pk_mul_f32 v[54:55], v[94:95], v[54:55]
	v_pk_add_f32 v[88:89], v[88:89], v[112:113]
	v_mov_b32_dpp v94, v58 row_shr:4 row_mask:0xf bank_mask:0xf bound_ctrl:1
	v_mov_b32_dpp v95, v59 row_shr:4 row_mask:0xf bank_mask:0xf bound_ctrl:1
	v_pk_fma_f32 v[52:53], v[92:93], v[92:93], v[52:53] neg_lo:[0,0,1] neg_hi:[0,0,1]
	v_mov_b32_dpp v92, v88 row_shr:4 row_mask:0xf bank_mask:0xf bound_ctrl:1
	v_mov_b32_dpp v93, v89 row_shr:4 row_mask:0xf bank_mask:0xf bound_ctrl:1
	v_pk_mul_f32 v[56:57], v[54:55], v[94:95]
	v_mov_b32_dpp v100, v98 row_shr:1 row_mask:0xf bank_mask:0xf bound_ctrl:1
	v_pk_fma_f32 v[56:57], v[52:53], v[92:93], v[56:57] neg_lo:[0,0,1] neg_hi:[0,0,1]
; #define SSM_SCAN_STEP(D, SQ) { _Pragma("unroll") for (int r = 0; r < 4; ++r) { \
;                     const float sr = dppf<DPP_SHR(D)>(Er[r]), si = dppf<DPP_SHR(D)>(Ei[r]); \
;                     Er[r] += mr[r] * sr - mi[r] * si; Ei[r] += mr[r] * si + mi[r] * sr; \
;                     if (SQ) { const float nr = mr[r] * mr[r] - mi[r] * mi[r], ni = 2.f * mr[r] * mi[r]; mr[r] = nr; mi[r] = ni; } } }
; template <bool PASS2>
; __device__ __forceinline__ void ssm_phase(const Params& p, const Frame& F0) {
;     ...
;             for (int i = 0; i < 4; ++i) {
;                 __builtin_amdgcn_sched_barrier(0);
;                 f32x4 Er = (f32x4){0.f, 0.f, 0.f, 0.f}, Ei = Er;
; #pragma unroll
;                 for (int ks = 0; ks < 4; ++ks) { Er = __builtin_amdgcn_mfma_f32_16x16x32_bf16(frag[(i * 4 + ks) * 64], uf[ks], Er, 0, 0, 0);
;                                                  Ei = __builtin_amdgcn_mfma_f32_16x16x32_bf16(frag[((i + 4) * 4 + ks) * 64], uf[ks], Ei, 0, 0, 0); }
;                 const f32x4 ma = m1t[8 * i], mb = m1t[8 * i + 1];
;                 float mr[4] = {ma[0], ma[2], mb[0], mb[2]}, mi[4] = {ma[1], ma[3], mb[1], mb[3]};
;                 float hr[4], hi[4];
; #pragma unroll
;                 for (int r = 0; r < 4; ++r) { hr[r] = dppf<DPP_ROR(1)>(xs[i][r]); hi[r] = dppf<DPP_ROR(1)>(xs[i + 4][r]);
;                     if (j == 0) { Er[r] += mr[r] * hr[r] - mi[r] * hi[r]; Ei[r] += mr[r] * hi[r] + mi[r] * hr[r]; } }
;     ...
;                 SSM_SCAN_STEP(1, 1) SSM_SCAN_STEP(2, 1) SSM_SCAN_STEP(4, 1) SSM_SCAN_STEP(8, 0)
	v_mov_b32_dpp v101, v99 row_shr:1 row_mask:0xf bank_mask:0xf bound_ctrl:1
	v_pk_add_f32 v[56:57], v[88:89], v[56:57]
	v_pk_mul_f32 v[88:89], v[52:53], v[94:95]
	v_mov_b32_e32 v94, v119
	v_pk_fma_f32 v[88:89], v[54:55], v[92:93], v[88:89]
	v_mov_b32_e32 v95, v121
	v_mov_b32_dpp v96, v90 row_shr:1 row_mask:0xf bank_mask:0xf bound_ctrl:1
	v_mov_b32_dpp v97, v91 row_shr:1 row_mask:0xf bank_mask:0xf bound_ctrl:1
	v_pk_add_f32 v[58:59], v[58:59], v[88:89]
	v_mov_b32_e32 v92, v118
	v_mov_b32_e32 v93, v120
	v_pk_mul_f32 v[88:89], v[94:95], v[100:101]
	s_nop 0
	v_pk_fma_f32 v[88:89], v[92:93], v[96:97], v[88:89] neg_lo:[0,0,1] neg_hi:[0,0,1]
	s_nop 0
	v_pk_add_f32 v[102:103], v[88:89], v[90:91]
	v_pk_mul_f32 v[88:89], v[120:121], v[120:121]
	v_pk_mul_f32 v[90:91], v[118:119], v[118:119]
	v_mov_b32_e32 v111, v88
	v_mov_b32_e32 v110, v90
	v_mov_b32_e32 v88, v91
	v_pk_add_f32 v[110:111], v[110:111], v[88:89] neg_lo:[0,1] neg_hi:[0,1]
	v_pk_add_f32 v[88:89], v[92:93], v[92:93]
	v_pk_mul_f32 v[92:93], v[92:93], v[100:101]
	v_pk_mul_f32 v[112:113], v[94:95], v[88:89]
	v_pk_fma_f32 v[92:93], v[94:95], v[96:97], v[92:93]
	v_mov_b32_dpp v114, v102 row_shr:2 row_mask:0xf bank_mask:0xf bound_ctrl:1
	v_pk_add_f32 v[92:93], v[92:93], v[98:99]
	v_mov_b32_dpp v115, v103 row_shr:2 row_mask:0xf bank_mask:0xf bound_ctrl:1
	v_pk_add_f32 v[90:91], v[110:111], v[110:111]
	v_mov_b32_dpp v94, v92 row_shr:2 row_mask:0xf bank_mask:0xf bound_ctrl:1
	v_mov_b32_dpp v95, v93 row_shr:2 row_mask:0xf bank_mask:0xf bound_ctrl:1
	v_pk_mul_f32 v[96:97], v[112:113], v[94:95]
	v_pk_mul_f32 v[94:95], v[110:111], v[94:95]
	v_pk_fma_f32 v[96:97], v[110:111], v[114:115], v[96:97] neg_lo:[0,0,1] neg_hi:[0,0,1]
	v_pk_fma_f32 v[94:95], v[112:113], v[114:115], v[94:95]
	v_pk_mul_f32 v[88:89], v[112:113], v[112:113]
	v_pk_add_f32 v[94:95], v[92:93], v[94:95]
	v_pk_mul_f32 v[90:91], v[112:113], v[90:91]
	v_pk_add_f32 v[96:97], v[102:103], v[96:97]
	v_mov_b32_dpp v100, v94 row_shr:4 row_mask:0xf bank_mask:0xf bound_ctrl:1
	v_mov_b32_dpp v101, v95 row_shr:4 row_mask:0xf bank_mask:0xf bound_ctrl:1
	v_pk_fma_f32 v[88:89], v[110:111], v[110:111], v[88:89] neg_lo:[0,0,1] neg_hi:[0,0,1]
	v_mov_b32_dpp v98, v96 row_shr:4 row_mask:0xf bank_mask:0xf bound_ctrl:1
	v_mov_b32_dpp v99, v97 row_shr:4 row_mask:0xf bank_mask:0xf bound_ctrl:1
	v_pk_mul_f32 v[92:93], v[90:91], v[100:101]
	s_nop 0
	v_pk_fma_f32 v[92:93], v[88:89], v[98:99], v[92:93] neg_lo:[0,0,1] neg_hi:[0,0,1]
	s_nop 0
	v_pk_add_f32 v[92:93], v[96:97], v[92:93]
	v_pk_mul_f32 v[96:97], v[88:89], v[100:101]
	v_mov_b32_dpp v100, v58 row_shr:8 row_mask:0xf bank_mask:0xf bound_ctrl:1
	v_pk_fma_f32 v[96:97], v[90:91], v[98:99], v[96:97]
	v_mov_b32_dpp v101, v59 row_shr:8 row_mask:0xf bank_mask:0xf bound_ctrl:1
	v_pk_add_f32 v[96:97], v[94:95], v[96:97]
	v_mov_b32_dpp v94, v56 row_shr:8 row_mask:0xf bank_mask:0xf bound_ctrl:1
	v_mov_b32_dpp v95, v57 row_shr:8 row_mask:0xf bank_mask:0xf bound_ctrl:1
	v_mov_b32_dpp v98, v92 row_shr:8 row_mask:0xf bank_mask:0xf bound_ctrl:1
	v_mov_b32_dpp v102, v96 row_shr:8 row_mask:0xf bank_mask:0xf bound_ctrl:1
	v_mov_b32_dpp v99, v93 row_shr:8 row_mask:0xf bank_mask:0xf bound_ctrl:1
	v_mov_b32_dpp v103, v97 row_shr:8 row_mask:0xf bank_mask:0xf bound_ctrl:1
	v_mov_b32_dpp v47, v47 row_ror:1 row_mask:0xf bank_mask:0xf bound_ctrl:1
	v_mfma_f32_16x16x32_bf16 v[110:113], v[178:181], v[12:15], 0
	v_mfma_f32_16x16x32_bf16 v[12:15], v[244:247], v[12:15], 0
	v_mfma_f32_16x16x32_bf16 v[110:113], v[182:185], v[4:7], v[110:113]
	v_mfma_f32_16x16x32_bf16 v[4:7], v[248:251], v[4:7], v[12:15]
	s_nop 2
	v_mfma_f32_16x16x32_bf16 v[12:15], v[186:189], v[8:11], v[110:113]
	s_nop 2
	ds_read_b128 v[110:113], v105 offset:30720
	s_waitcnt lgkmcnt(0)
	v_mfma_f32_16x16x32_bf16 v[4:7], v[110:113], v[8:11], v[4:7]
	v_mov_b32_dpp v111, v46 row_ror:1 row_mask:0xf bank_mask:0xf bound_ctrl:1
	v_mov_b32_dpp v110, v44 row_ror:1 row_mask:0xf bank_mask:0xf bound_ctrl:1
	v_mfma_f32_16x16x32_bf16 v[8:11], v[190:193], v[0:3], v[12:15]
	s_nop 2
	ds_read_b128 v[12:15], v105 offset:31744
	v_mov_b32_dpp v46, v45 row_ror:1 row_mask:0xf bank_mask:0xf bound_ctrl:1
	s_waitcnt lgkmcnt(0)
	v_mfma_f32_16x16x32_bf16 v[0:3], v[12:15], v[0:3], v[4:7]
	s_nop 2
	ds_read_b128 v[4:7], v109 offset:384
	ds_read_b128 v[12:15], v109 offset:400
	s_waitcnt lgkmcnt(1)
	v_pk_mul_f32 v[112:113], v[4:5], v[110:111] op_sel:[0,1] op_sel_hi:[1,0]
	s_nop 0
	v_sub_f32_e32 v44, v112, v113
	v_pk_mul_f32 v[110:111], v[4:5], v[110:111]
	v_add_f32_e32 v112, v8, v44
	v_add_f32_e32 v44, v111, v110
	v_add_f32_e32 v110, v0, v44
	v_pk_mul_f32 v[44:45], v[6:7], v[46:47] op_sel:[0,1] op_sel_hi:[1,0]
	v_mov_b32_e32 v114, v5
	v_sub_f32_e32 v44, v44, v45
	v_add_f32_e32 v111, v44, v9
	v_pk_mul_f32 v[44:45], v[6:7], v[46:47]
	v_mov_b32_e32 v115, v7
	v_add_f32_e32 v44, v45, v44
	v_add_f32_e32 v113, v44, v1
	v_mov_b32_dpp v45, v50 row_ror:1 row_mask:0xf bank_mask:0xf bound_ctrl:1
	v_mov_b32_dpp v44, v48 row_ror:1 row_mask:0xf bank_mask:0xf bound_ctrl:1
	s_waitcnt lgkmcnt(0)
; #define SSM_SCAN_STEP(D, SQ) { _Pragma("unroll") for (int r = 0; r < 4; ++r) { \
;                     const float sr = dppf<DPP_SHR(D)>(Er[r]), si = dppf<DPP_SHR(D)>(Ei[r]); \
;                     Er[r] += mr[r] * sr - mi[r] * si; Ei[r] += mr[r] * si + mi[r] * sr; \
;                     if (SQ) { const float nr = mr[r] * mr[r] - mi[r] * mi[r], ni = 2.f * mr[r] * mi[r]; mr[r] = nr; mi[r] = ni; } } }
; template <bool PASS2>
; __device__ __forceinline__ void ssm_phase(const Params& p, const Frame& F0) {
;     ...
;                 for (int r = 0; r < 4; ++r) { hr[r] = dppf<DPP_ROR(1)>(xs[i][r]); hi[r] = dppf<DPP_ROR(1)>(xs[i + 4][r]);
;                     if (j == 0) { Er[r] += mr[r] * hr[r] - mi[r] * hi[r]; Ei[r] += mr[r] * hi[r] + mi[r] * hr[r]; } }
;     ...
;                 SSM_SCAN_STEP(1, 1) SSM_SCAN_STEP(2, 1) SSM_SCAN_STEP(4, 1) SSM_SCAN_STEP(8, 0)
;     ...
;         if constexpr (!PASS2) { if (j == 15) { float* wb = Wst + (size_t)((g * 2 + b) * 32 + wch) * 128;
	v_pk_mul_f32 v[46:47], v[12:13], v[44:45] op_sel:[0,1] op_sel_hi:[1,0]
	v_pk_mul_f32 v[44:45], v[12:13], v[44:45]
	v_sub_f32_e32 v46, v46, v47
	v_add_f32_e32 v44, v45, v44
	v_add_f32_e32 v50, v44, v2
	v_mov_b32_dpp v45, v51 row_ror:1 row_mask:0xf bank_mask:0xf bound_ctrl:1
	v_mov_b32_dpp v44, v49 row_ror:1 row_mask:0xf bank_mask:0xf bound_ctrl:1
	v_add_f32_e32 v48, v46, v10
	v_pk_mul_f32 v[46:47], v[14:15], v[44:45] op_sel:[0,1] op_sel_hi:[1,0]
	v_pk_mul_f32 v[44:45], v[14:15], v[44:45]
	v_sub_f32_e32 v46, v46, v47
	v_add_f32_e32 v49, v46, v11
	v_add_f32_e32 v44, v45, v44
	v_cndmask_b32_e64 v47, v1, v113, s[6:7]
	v_cndmask_b32_e64 v46, v0, v110, s[6:7]
	v_add_f32_e32 v44, v44, v3
	v_cndmask_b32_e64 v11, v11, v49, s[6:7]
	v_cndmask_b32_e64 v10, v10, v48, s[6:7]
	v_cndmask_b32_e64 v1, v9, v111, s[6:7]
	v_cndmask_b32_e64 v0, v8, v112, s[6:7]
	v_mov_b32_dpp v48, v46 row_shr:1 row_mask:0xf bank_mask:0xf bound_ctrl:1
	v_mov_b32_dpp v49, v47 row_shr:1 row_mask:0xf bank_mask:0xf bound_ctrl:1
	v_cndmask_b32_e64 v45, v3, v44, s[6:7]
	v_cndmask_b32_e64 v44, v2, v50, s[6:7]
	v_mov_b32_dpp v8, v0 row_shr:1 row_mask:0xf bank_mask:0xf bound_ctrl:1
	v_mov_b32_dpp v9, v1 row_shr:1 row_mask:0xf bank_mask:0xf bound_ctrl:1
	v_mov_b32_e32 v112, v4
	v_mov_b32_e32 v113, v6
	v_pk_mul_f32 v[2:3], v[114:115], v[48:49]
	v_pk_mul_f32 v[48:49], v[112:113], v[48:49]
	v_pk_fma_f32 v[2:3], v[112:113], v[8:9], v[2:3] neg_lo:[0,0,1] neg_hi:[0,0,1]
	v_pk_fma_f32 v[8:9], v[114:115], v[8:9], v[48:49]
	v_pk_add_f32 v[116:117], v[2:3], v[0:1]
	v_pk_mul_f32 v[0:1], v[6:7], v[6:7]
	v_pk_mul_f32 v[2:3], v[4:5], v[4:5]
	v_mov_b32_e32 v5, v0
	v_mov_b32_e32 v4, v2
	v_mov_b32_e32 v0, v3
	v_pk_add_f32 v[4:5], v[4:5], v[0:1] neg_lo:[0,1] neg_hi:[0,1]
	v_pk_add_f32 v[0:1], v[112:113], v[112:113]
	v_pk_add_f32 v[8:9], v[8:9], v[46:47]
	v_pk_mul_f32 v[6:7], v[114:115], v[0:1]
	v_mov_b32_dpp v118, v116 row_shr:2 row_mask:0xf bank_mask:0xf bound_ctrl:1
	v_mov_b32_dpp v46, v8 row_shr:2 row_mask:0xf bank_mask:0xf bound_ctrl:1
	v_mov_b32_dpp v47, v9 row_shr:2 row_mask:0xf bank_mask:0xf bound_ctrl:1
	v_mov_b32_dpp v119, v117 row_shr:2 row_mask:0xf bank_mask:0xf bound_ctrl:1
	v_pk_mul_f32 v[0:1], v[6:7], v[6:7]
	v_pk_mul_f32 v[48:49], v[6:7], v[46:47]
	v_pk_fma_f32 v[0:1], v[4:5], v[4:5], v[0:1] neg_lo:[0,0,1] neg_hi:[0,0,1]
	v_pk_add_f32 v[2:3], v[4:5], v[4:5]
	v_pk_fma_f32 v[48:49], v[4:5], v[118:119], v[48:49] neg_lo:[0,0,1] neg_hi:[0,0,1]
	v_pk_mul_f32 v[4:5], v[4:5], v[46:47]
	v_pk_mul_f32 v[2:3], v[6:7], v[2:3]
	v_pk_fma_f32 v[4:5], v[6:7], v[118:119], v[4:5]
	v_pk_add_f32 v[48:49], v[48:49], v[116:117]
	v_pk_add_f32 v[6:7], v[8:9], v[4:5]
	v_mov_b32_dpp v110, v44 row_shr:1 row_mask:0xf bank_mask:0xf bound_ctrl:1
	v_mov_b32_dpp v8, v48 row_shr:4 row_mask:0xf bank_mask:0xf bound_ctrl:1
	v_mov_b32_dpp v46, v6 row_shr:4 row_mask:0xf bank_mask:0xf bound_ctrl:1
	v_mov_b32_dpp v47, v7 row_shr:4 row_mask:0xf bank_mask:0xf bound_ctrl:1
	v_mov_b32_dpp v9, v49 row_shr:4 row_mask:0xf bank_mask:0xf bound_ctrl:1
	v_pk_mul_f32 v[4:5], v[2:3], v[46:47]
	v_pk_mul_f32 v[46:47], v[0:1], v[46:47]
	v_pk_fma_f32 v[4:5], v[0:1], v[8:9], v[4:5] neg_lo:[0,0,1] neg_hi:[0,0,1]
	v_mov_b32_dpp v111, v45 row_shr:1 row_mask:0xf bank_mask:0xf bound_ctrl:1
	v_pk_add_f32 v[4:5], v[48:49], v[4:5]
	v_pk_fma_f32 v[8:9], v[2:3], v[8:9], v[46:47]
	v_mov_b32_e32 v48, v13
	v_mov_b32_e32 v49, v15
	v_mov_b32_dpp v50, v10 row_shr:1 row_mask:0xf bank_mask:0xf bound_ctrl:1
	v_mov_b32_dpp v51, v11 row_shr:1 row_mask:0xf bank_mask:0xf bound_ctrl:1
	v_pk_add_f32 v[6:7], v[6:7], v[8:9]
	v_mov_b32_e32 v46, v12
	v_mov_b32_e32 v47, v14
	v_pk_mul_f32 v[8:9], v[48:49], v[110:111]
	s_nop 0
	v_pk_fma_f32 v[8:9], v[46:47], v[50:51], v[8:9] neg_lo:[0,0,1] neg_hi:[0,0,1]
	s_nop 0
	v_pk_add_f32 v[112:113], v[8:9], v[10:11]
	v_pk_mul_f32 v[8:9], v[14:15], v[14:15]
	v_pk_mul_f32 v[10:11], v[12:13], v[12:13]
	v_mov_b32_e32 v13, v8
	v_mov_b32_e32 v12, v10
	v_mov_b32_e32 v8, v11
	v_pk_add_f32 v[12:13], v[12:13], v[8:9] neg_lo:[0,1] neg_hi:[0,1]
	v_pk_add_f32 v[8:9], v[46:47], v[46:47]
	v_pk_mul_f32 v[46:47], v[46:47], v[110:111]
	v_pk_mul_f32 v[14:15], v[48:49], v[8:9]
	v_pk_fma_f32 v[46:47], v[48:49], v[50:51], v[46:47]
	v_mov_b32_dpp v114, v112 row_shr:2 row_mask:0xf bank_mask:0xf bound_ctrl:1
	v_pk_add_f32 v[44:45], v[46:47], v[44:45]
	v_mov_b32_dpp v115, v113 row_shr:2 row_mask:0xf bank_mask:0xf bound_ctrl:1
	v_pk_mul_f32 v[8:9], v[14:15], v[14:15]
	v_mov_b32_dpp v46, v44 row_shr:2 row_mask:0xf bank_mask:0xf bound_ctrl:1
	v_mov_b32_dpp v47, v45 row_shr:2 row_mask:0xf bank_mask:0xf bound_ctrl:1
	v_pk_mul_f32 v[48:49], v[14:15], v[46:47]
	v_pk_fma_f32 v[8:9], v[12:13], v[12:13], v[8:9] neg_lo:[0,0,1] neg_hi:[0,0,1]
	v_pk_add_f32 v[10:11], v[12:13], v[12:13]
	v_pk_fma_f32 v[48:49], v[12:13], v[114:115], v[48:49] neg_lo:[0,0,1] neg_hi:[0,0,1]
	v_pk_mul_f32 v[12:13], v[12:13], v[46:47]
	v_pk_mul_f32 v[10:11], v[14:15], v[10:11]
	v_pk_fma_f32 v[12:13], v[14:15], v[114:115], v[12:13]
	v_pk_add_f32 v[48:49], v[112:113], v[48:49]
	v_pk_add_f32 v[14:15], v[44:45], v[12:13]
	s_nop 0
	v_mov_b32_dpp v44, v48 row_shr:4 row_mask:0xf bank_mask:0xf bound_ctrl:1
	v_mov_b32_dpp v46, v14 row_shr:4 row_mask:0xf bank_mask:0xf bound_ctrl:1
	v_mov_b32_dpp v47, v15 row_shr:4 row_mask:0xf bank_mask:0xf bound_ctrl:1
	v_mov_b32_dpp v45, v49 row_shr:4 row_mask:0xf bank_mask:0xf bound_ctrl:1
	v_pk_mul_f32 v[12:13], v[10:11], v[46:47]
	v_pk_mul_f32 v[46:47], v[8:9], v[46:47]
	v_pk_fma_f32 v[12:13], v[8:9], v[44:45], v[12:13] neg_lo:[0,0,1] neg_hi:[0,0,1]
	v_pk_fma_f32 v[44:45], v[10:11], v[44:45], v[46:47]
	v_pk_add_f32 v[12:13], v[48:49], v[12:13]
	v_pk_add_f32 v[44:45], v[14:15], v[44:45]
	v_mov_b32_dpp v14, v4 row_shr:8 row_mask:0xf bank_mask:0xf bound_ctrl:1
	v_mov_b32_dpp v46, v6 row_shr:8 row_mask:0xf bank_mask:0xf bound_ctrl:1
	v_mov_b32_dpp v15, v5 row_shr:8 row_mask:0xf bank_mask:0xf bound_ctrl:1
	v_mov_b32_dpp v47, v7 row_shr:8 row_mask:0xf bank_mask:0xf bound_ctrl:1
	v_mov_b32_dpp v48, v12 row_shr:8 row_mask:0xf bank_mask:0xf bound_ctrl:1
	v_mov_b32_dpp v50, v44 row_shr:8 row_mask:0xf bank_mask:0xf bound_ctrl:1
	v_mov_b32_dpp v49, v13 row_shr:8 row_mask:0xf bank_mask:0xf bound_ctrl:1
	v_mov_b32_dpp v51, v45 row_shr:8 row_mask:0xf bank_mask:0xf bound_ctrl:1
	s_and_saveexec_b64 s[0:1], s[8:9]
	s_cbranch_execz .LBB0_520
; #define SSM_SCAN_STEP(D, SQ) { _Pragma("unroll") for (int r = 0; r < 4; ++r) { \
;                     const float sr = dppf<DPP_SHR(D)>(Er[r]), si = dppf<DPP_SHR(D)>(Ei[r]); \
;                     Er[r] += mr[r] * sr - mi[r] * si; Ei[r] += mr[r] * si + mi[r] * sr; \
;                     if (SQ) { const float nr = mr[r] * mr[r] - mi[r] * mi[r], ni = 2.f * mr[r] * mi[r]; mr[r] = nr; mi[r] = ni; } } }
; template <bool PASS2>
; __device__ __forceinline__ void ssm_phase(const Params& p, const Frame& F0) {
;     ...
;                 SSM_SCAN_STEP(1, 1) SSM_SCAN_STEP(2, 1) SSM_SCAN_STEP(4, 1) SSM_SCAN_STEP(8, 0)
;     ...
;         if constexpr (!PASS2) { if (j == 15) { float* wb = Wst + (size_t)((g * 2 + b) * 32 + wch) * 128;
; #pragma unroll
;                 for (int i = 0; i < 4; ++i) { *(f32x4*)(wb + 16 * i + 4 * gq) = xs[i]; *(f32x4*)(wb + 64 + 16 * i + 4 * gq) = xs[i + 4]; } } }
	v_pk_mul_f32 v[112:113], v[54:55], v[54:55]
	v_pk_add_f32 v[110:111], v[52:53], v[52:53]
	v_pk_mul_f32 v[116:117], v[90:91], v[90:91]
	v_pk_fma_f32 v[112:113], v[52:53], v[52:53], v[112:113] neg_lo:[0,0,1] neg_hi:[0,0,1]
	v_pk_add_f32 v[114:115], v[88:89], v[88:89]
	v_pk_mul_f32 v[110:111], v[54:55], v[110:111]
	v_pk_fma_f32 v[88:89], v[88:89], v[88:89], v[116:117] neg_lo:[0,0,1] neg_hi:[0,0,1]
	v_pk_mul_f32 v[52:53], v[112:113], v[100:101]
	v_pk_mul_f32 v[90:91], v[90:91], v[114:115]
	v_pk_mul_f32 v[54:55], v[88:89], v[102:103]
	v_pk_fma_f32 v[52:53], v[110:111], v[94:95], v[52:53]
	v_pk_fma_f32 v[54:55], v[90:91], v[98:99], v[54:55]
	v_pk_add_f32 v[52:53], v[58:59], v[52:53]
	v_pk_mul_f32 v[58:59], v[110:111], v[100:101]
	v_pk_mul_f32 v[90:91], v[90:91], v[102:103]
	v_pk_fma_f32 v[58:59], v[112:113], v[94:95], v[58:59] neg_lo:[0,0,1] neg_hi:[0,0,1]
	v_pk_fma_f32 v[88:89], v[88:89], v[98:99], v[90:91] neg_lo:[0,0,1] neg_hi:[0,0,1]
	v_pk_mul_f32 v[90:91], v[62:63], v[62:63]
	v_pk_add_f32 v[56:57], v[56:57], v[58:59]
	v_pk_add_f32 v[58:59], v[92:93], v[88:89]
	v_pk_add_f32 v[88:89], v[60:61], v[60:61]
	v_pk_mul_f32 v[94:95], v[74:75], v[74:75]
	v_pk_fma_f32 v[90:91], v[60:61], v[60:61], v[90:91] neg_lo:[0,0,1] neg_hi:[0,0,1]
	v_pk_add_f32 v[92:93], v[72:73], v[72:73]
	v_pk_mul_f32 v[88:89], v[62:63], v[88:89]
	v_pk_fma_f32 v[72:73], v[72:73], v[72:73], v[94:95] neg_lo:[0,0,1] neg_hi:[0,0,1]
	v_pk_mul_f32 v[60:61], v[90:91], v[84:85]
	v_pk_mul_f32 v[74:75], v[74:75], v[92:93]
	v_pk_mul_f32 v[62:63], v[72:73], v[86:87]
	v_pk_fma_f32 v[60:61], v[88:89], v[78:79], v[60:61]
	v_pk_fma_f32 v[62:63], v[74:75], v[82:83], v[62:63]
	v_pk_add_f32 v[60:61], v[68:69], v[60:61]
	v_pk_mul_f32 v[68:69], v[88:89], v[84:85]
	v_pk_mul_f32 v[74:75], v[74:75], v[86:87]
	v_pk_fma_f32 v[68:69], v[90:91], v[78:79], v[68:69] neg_lo:[0,0,1] neg_hi:[0,0,1]
	v_pk_fma_f32 v[72:73], v[72:73], v[82:83], v[74:75] neg_lo:[0,0,1] neg_hi:[0,0,1]
	v_pk_mul_f32 v[74:75], v[18:19], v[18:19]
	v_pk_add_f32 v[66:67], v[66:67], v[68:69]
	v_pk_add_f32 v[68:69], v[76:77], v[72:73]
	v_pk_add_f32 v[72:73], v[16:17], v[16:17]
	v_pk_mul_f32 v[78:79], v[26:27], v[26:27]
	v_pk_fma_f32 v[74:75], v[16:17], v[16:17], v[74:75] neg_lo:[0,0,1] neg_hi:[0,0,1]
	v_pk_add_f32 v[76:77], v[24:25], v[24:25]
	v_pk_mul_f32 v[72:73], v[18:19], v[72:73]
	v_pk_fma_f32 v[24:25], v[24:25], v[24:25], v[78:79] neg_lo:[0,0,1] neg_hi:[0,0,1]
	v_pk_mul_f32 v[16:17], v[74:75], v[64:65]
	v_pk_mul_f32 v[26:27], v[26:27], v[76:77]
	v_pk_mul_f32 v[18:19], v[24:25], v[70:71]
	v_pk_fma_f32 v[16:17], v[72:73], v[30:31], v[16:17]
	v_pk_fma_f32 v[18:19], v[26:27], v[34:35], v[18:19]
	v_pk_add_f32 v[16:17], v[22:23], v[16:17]
	v_pk_mul_f32 v[22:23], v[72:73], v[64:65]
	v_pk_mul_f32 v[26:27], v[26:27], v[70:71]
	v_pk_fma_f32 v[22:23], v[74:75], v[30:31], v[22:23] neg_lo:[0,0,1] neg_hi:[0,0,1]
	v_pk_fma_f32 v[24:25], v[24:25], v[34:35], v[26:27] neg_lo:[0,0,1] neg_hi:[0,0,1]
	v_pk_mul_f32 v[30:31], v[2:3], v[2:3]
	v_pk_add_f32 v[20:21], v[20:21], v[22:23]
	v_pk_add_f32 v[22:23], v[28:29], v[24:25]
	v_pk_mul_f32 v[26:27], v[10:11], v[10:11]
	v_pk_add_f32 v[28:29], v[0:1], v[0:1]
	v_pk_fma_f32 v[30:31], v[0:1], v[0:1], v[30:31] neg_lo:[0,0,1] neg_hi:[0,0,1]
	s_lshl_b32 s10, s16, 6
	s_lshl_b32 s16, s17, 5
	v_pk_add_f32 v[24:25], v[8:9], v[8:9]
	v_pk_mul_f32 v[28:29], v[2:3], v[28:29]
	v_pk_fma_f32 v[8:9], v[8:9], v[8:9], v[26:27] neg_lo:[0,0,1] neg_hi:[0,0,1]
	v_pk_mul_f32 v[0:1], v[30:31], v[46:47]
	s_add_i32 s16, s18, s16
	v_pk_mul_f32 v[10:11], v[10:11], v[24:25]
	v_pk_mul_f32 v[2:3], v[8:9], v[50:51]
	v_pk_fma_f32 v[0:1], v[28:29], v[14:15], v[0:1]
	s_add_i32 s16, s16, s10
	v_pk_fma_f32 v[2:3], v[10:11], v[48:49], v[2:3]
	v_pk_add_f32 v[0:1], v[6:7], v[0:1]
	v_pk_mul_f32 v[6:7], v[28:29], v[46:47]
	v_pk_mul_f32 v[10:11], v[10:11], v[50:51]
	s_ashr_i32 s17, s16, 31
	v_pk_fma_f32 v[6:7], v[30:31], v[14:15], v[6:7] neg_lo:[0,0,1] neg_hi:[0,0,1]
	v_pk_fma_f32 v[8:9], v[8:9], v[48:49], v[10:11] neg_lo:[0,0,1] neg_hi:[0,0,1]
	s_lshl_b64 s[16:17], s[16:17], 9
	v_pk_add_f32 v[4:5], v[4:5], v[6:7]
	v_pk_add_f32 v[6:7], v[12:13], v[8:9]
	v_lshl_add_u64 v[8:9], v[40:41], 0, s[16:17]
	v_pk_add_f32 v[54:55], v[96:97], v[54:55]
	v_pk_add_f32 v[62:63], v[80:81], v[62:63]
	v_pk_add_f32 v[18:19], v[32:33], v[18:19]
	v_pk_add_f32 v[2:3], v[44:45], v[2:3]
	global_store_dwordx4 v[8:9], v[20:23], off
	global_store_dwordx4 v[8:9], v[16:19], off offset:256
	global_store_dwordx4 v[8:9], v[66:69], off offset:64
	global_store_dwordx4 v[8:9], v[60:63], off offset:320
	global_store_dwordx4 v[8:9], v[56:59], off offset:128
	global_store_dwordx4 v[8:9], v[52:55], off offset:384
	global_store_dwordx4 v[8:9], v[4:7], off offset:192
	global_store_dwordx4 v[8:9], v[0:3], off offset:448
	s_branch .LBB0_520
